# P2 P9 P11 residual epilogues: base loads prefetched in two batches of 4 rows, per-row vmcnt(0) waits removed (on top of P10 edit)
# speedup vs baseline: 1.0007x; 1.0007x over previous
; DI unsigned pk2(float lo, float hi) { typedef float v2f __attribute__((ext_vector_type(2))); typedef __bf16 v2b __attribute__((ext_vector_type(2))); v2f v = {lo, hi}; v2b b = __builtin_convertvector(v, v2b); return __builtin_bit_cast(unsigned, b); }
; DI float bflo(unsigned w) { return __uint_as_float(w << 16); }
; DI float bfhi(unsigned w) { return __uint_as_float(w & 0xffff0000u); }
; DI void atomic_addf(float* p, float v) { __builtin_amdgcn_global_atomic_fadd_f32((__attribute__((address_space(1))) float*)p, v); }
; DI float quad_sum(float s) { s += __shfl_xor(s, 16); s += __shfl_xor(s, 32); return s; }
;     DI void operator()(const f32x4 (&acc)[2][2][4][2], const Unit& u, int wr, int wc, int fr, int fq) const {
;     ...
;                 const int row = row0 + ai * 128 + m * 16; float ss = 0.f;
;                 const float bs = (B16 && base) ? base[row] : 1.0f;
; #pragma unroll
;                 for (int bj = 0; bj < 2; ++bj) {
;                     const size_t off = (size_t)row * DM + col0 + bj * 128;
;                     f32x4 b0, b1;
;                     if (B16) { const u32x4 bb = *(const u32x4*)(base16 + off); b0 = (f32x4){bflo(bb.x), bfhi(bb.x), bflo(bb.y), bfhi(bb.y)}; b1 = (f32x4){bflo(bb.z), bfhi(bb.z), bflo(bb.w), bfhi(bb.w)}; b0 = b0 * bs; b1 = b1 * bs; }
;                     else { b0 = *(const f32x4*)(base + off); b1 = *(const f32x4*)(base + off + 4); }
;                     const f32x4 o0 = b0 + acc[ai][bj][m][0] * alpha, o1 = b1 + acc[ai][bj][m][1] * alpha;
;                     if (WOUT) { *(f32x4*)(out + off) = o0; *(f32x4*)(out + off + 4) = o1; }
;                     if (WB) { ss += (o0[0] * o0[0] + o0[1] * o0[1]) + (o0[2] * o0[2] + o0[3] * o0[3]) + (o1[0] * o1[0] + o1[1] * o1[1]) + (o1[2] * o1[2] + o1[3] * o1[3]);
;                         u32x4 w; w.x = pk2(o0[0], o0[1]); w.y = pk2(o0[2], o0[3]); w.z = pk2(o1[0], o1[1]); w.w = pk2(o1[2], o1[3]); *(u32x4*)(xb + off) = w; }
;                 }
;                 if (WB) { ss = quad_sum(ss); if (fq == 0) atomic_addf(P + row, ss); }
.LBB0_545:
	v_lshl_add_u32 v150, s13, 8, v129
	v_lshl_or_b32 v148, s12, 8, v154
	v_ashrrev_i32_e32 v151, 31, v150
	v_ashrrev_i32_e32 v149, 31, v148
	v_lshlrev_b64 v[152:153], 10, v[150:151]
	v_lshl_add_u64 v[152:153], v[152:153], 0, v[148:149]
	v_lshlrev_b64 v[170:171], 1, v[152:153]
	v_lshl_add_u64 v[152:153], s[14:15], 0, v[170:171]
	v_lshl_add_u64 v[174:175], s[34:35], 0, v[170:171]
	v_mov_b32_e32 v190, v170
	v_mov_b32_e32 v191, v171
	v_lshl_add_u64 v[188:189], v[150:151], 2, s[10:11]
	v_mov_b32_e32 v184, v190
	v_mov_b32_e32 v185, v191
	v_lshl_add_u64 v[186:187], s[14:15], 0, v[184:185]
	global_load_dwordx4 v[198:201], v[186:187], off
	global_load_dwordx4 v[202:205], v[186:187], off offset:256
	global_load_dword v230, v[188:189], off offset:0
	v_add_u32_e32 v184, 0x8000, v190
	v_mov_b32_e32 v185, v191
	v_lshl_add_u64 v[186:187], s[14:15], 0, v[184:185]
	global_load_dwordx4 v[206:209], v[186:187], off
	global_load_dwordx4 v[210:213], v[186:187], off offset:256
	global_load_dword v232, v[188:189], off offset:64
	v_add_u32_e32 v184, 0x10000, v190
	v_mov_b32_e32 v185, v191
	v_lshl_add_u64 v[186:187], s[14:15], 0, v[184:185]
	global_load_dwordx4 v[214:217], v[186:187], off
	global_load_dwordx4 v[218:221], v[186:187], off offset:256
	global_load_dword v234, v[188:189], off offset:128
	v_add_u32_e32 v184, 0x18000, v190
	v_mov_b32_e32 v185, v191
	v_lshl_add_u64 v[186:187], s[14:15], 0, v[184:185]
	global_load_dwordx4 v[222:225], v[186:187], off
	global_load_dwordx4 v[226:229], v[186:187], off offset:256
	global_load_dword v236, v[188:189], off offset:192
	v_or_b32_e32 v170, 0x100, v170
	v_lshl_add_u64 v[160:161], s[14:15], 0, v[170:171]
	s_nop 0
	s_nop 0
	v_lshl_add_u64 v[152:153], v[150:151], 2, s[10:11]
	s_nop 0
	v_and_b32_e32 v160, 64, v158
	v_xor_b32_e32 v159, 16, v158
	v_add_u32_e32 v160, 64, v160
	v_xor_b32_e32 v161, 32, v158
	v_cmp_lt_i32_e32 vcc, v159, v160
	s_waitcnt vmcnt(0)
	v_lshlrev_b32_e32 v176, 16, v198
	v_and_b32_e32 v177, 0xffff0000, v198
	v_lshlrev_b32_e32 v162, 16, v199
	v_and_b32_e32 v163, 0xffff0000, v199
	v_lshlrev_b32_e32 v178, 16, v200
	v_and_b32_e32 v179, 0xffff0000, v200
	v_lshlrev_b32_e32 v164, 16, v201
	v_and_b32_e32 v165, 0xffff0000, v201
	v_pk_mul_f32 v[176:177], v[230:231], v[176:177] op_sel_hi:[0,1]
	v_lshlrev_b32_e32 v180, 16, v202
	v_and_b32_e32 v181, 0xffff0000, v202
	v_lshlrev_b32_e32 v166, 16, v203
	v_and_b32_e32 v167, 0xffff0000, v203
	v_cndmask_b32_e32 v159, v158, v159, vcc
	v_cmp_lt_i32_e32 vcc, v161, v160
	v_pk_mul_f32 v[162:163], v[230:231], v[162:163] op_sel_hi:[0,1]
	v_pk_mul_f32 v[178:179], v[230:231], v[178:179] op_sel_hi:[0,1]
	v_pk_mul_f32 v[164:165], v[230:231], v[164:165] op_sel_hi:[0,1]
	v_lshlrev_b32_e32 v182, 16, v204
	v_and_b32_e32 v183, 0xffff0000, v204
	v_lshlrev_b32_e32 v168, 16, v205
	v_and_b32_e32 v169, 0xffff0000, v205
	v_pk_fma_f32 v[124:125], v[124:125], 0.5, v[176:177] op_sel_hi:[1,0,1]
	v_pk_mul_f32 v[176:177], v[230:231], v[180:181] op_sel_hi:[0,1]
	v_pk_mul_f32 v[166:167], v[230:231], v[166:167] op_sel_hi:[0,1]
	v_cndmask_b32_e32 v161, v158, v161, vcc
	v_pk_fma_f32 v[126:127], v[126:127], 0.5, v[162:163] op_sel_hi:[1,0,1]
	v_pk_fma_f32 v[162:163], v[122:123], 0.5, v[164:165] op_sel_hi:[1,0,1]
	v_pk_fma_f32 v[164:165], v[120:121], 0.5, v[178:179] op_sel_hi:[1,0,1]
	v_pk_mul_f32 v[178:179], v[230:231], v[182:183] op_sel_hi:[0,1]
	v_pk_mul_f32 v[168:169], v[230:231], v[168:169] op_sel_hi:[0,1]
	v_pk_fma_f32 v[118:119], v[118:119], 0.5, v[166:167] op_sel_hi:[1,0,1]
	v_pk_fma_f32 v[116:117], v[116:117], 0.5, v[176:177] op_sel_hi:[1,0,1]
	v_lshlrev_b32_e32 v160, 2, v159
	v_lshlrev_b32_e32 v159, 2, v161
	v_mul_f32_e32 v123, v125, v125
	v_mul_f32_e32 v161, v127, v127
	v_pk_fma_f32 v[166:167], v[114:115], 0.5, v[168:169] op_sel_hi:[1,0,1]
	v_pk_fma_f32 v[168:169], v[112:113], 0.5, v[178:179] op_sel_hi:[1,0,1]
	v_mul_f32_e32 v112, v117, v117
	v_mul_f32_e32 v113, v119, v119
	v_mul_f32_e32 v172, v165, v165
	v_fmac_f32_e32 v123, v124, v124
	v_fmac_f32_e32 v161, v126, v126
	v_mul_f32_e32 v114, v169, v169
	v_fmac_f32_e32 v112, v116, v116
	v_fmac_f32_e32 v113, v118, v118
	v_mul_f32_e32 v173, v163, v163
	v_fmac_f32_e32 v172, v164, v164
	v_mul_f32_e32 v115, v167, v167
	v_add_f32_e32 v123, v123, v161
	v_fmac_f32_e32 v114, v168, v168
	v_add_f32_e32 v112, v112, v113
	v_fmac_f32_e32 v173, v162, v162
	v_add_f32_e32 v123, v172, v123
	v_add_f32_e32 v112, v114, v112
	v_fmac_f32_e32 v115, v166, v166
	v_add_f32_e32 v113, v173, v123
	v_add_f32_e32 v112, v115, v112
	v_add_f32_e32 v112, v113, v112
	ds_bpermute_b32 v113, v160, v112
	v_cvt_pk_bf16_f32 v120, v124, v125
	v_cvt_pk_bf16_f32 v121, v126, v127
	v_cvt_pk_bf16_f32 v122, v164, v165
	v_cvt_pk_bf16_f32 v123, v162, v163
	s_waitcnt lgkmcnt(0)
	v_add_f32_e32 v112, v112, v113
	ds_bpermute_b32 v113, v159, v112
	v_cvt_pk_bf16_f32 v114, v116, v117
	v_cvt_pk_bf16_f32 v115, v118, v119
	v_cvt_pk_bf16_f32 v116, v168, v169
	v_cvt_pk_bf16_f32 v117, v166, v167
	v_lshl_add_u64 v[118:119], s[34:35], 0, v[170:171]
	flat_store_dwordx4 v[174:175], v[120:123]
	flat_store_dwordx4 v[118:119], v[114:117]
	s_and_saveexec_b64 s[12:13], s[2:3]
	v_readlane_b32 s88, v249, 57
	v_readlane_b32 s89, v249, 58
	s_cbranch_execz .LBB0_547
	v_lshl_add_u64 v[114:115], v[150:151], 2, s[42:43]
	s_waitcnt lgkmcnt(0)
	v_add_f32_e32 v112, v112, v113
	global_atomic_add_f32 v[114:115], v112, off
; DI unsigned pk2(float lo, float hi) { typedef float v2f __attribute__((ext_vector_type(2))); typedef __bf16 v2b __attribute__((ext_vector_type(2))); v2f v = {lo, hi}; v2b b = __builtin_convertvector(v, v2b); return __builtin_bit_cast(unsigned, b); }
; DI float bflo(unsigned w) { return __uint_as_float(w << 16); }
; DI float bfhi(unsigned w) { return __uint_as_float(w & 0xffff0000u); }
; DI void atomic_addf(float* p, float v) { __builtin_amdgcn_global_atomic_fadd_f32((__attribute__((address_space(1))) float*)p, v); }
; DI float quad_sum(float s) { s += __shfl_xor(s, 16); s += __shfl_xor(s, 32); return s; }
;     DI void operator()(const f32x4 (&acc)[2][2][4][2], const Unit& u, int wr, int wc, int fr, int fq) const {
;     ...
;                 const int row = row0 + ai * 128 + m * 16; float ss = 0.f;
;                 const float bs = (B16 && base) ? base[row] : 1.0f;
; #pragma unroll
;                 for (int bj = 0; bj < 2; ++bj) {
;                     const size_t off = (size_t)row * DM + col0 + bj * 128;
;                     f32x4 b0, b1;
;                     if (B16) { const u32x4 bb = *(const u32x4*)(base16 + off); b0 = (f32x4){bflo(bb.x), bfhi(bb.x), bflo(bb.y), bfhi(bb.y)}; b1 = (f32x4){bflo(bb.z), bfhi(bb.z), bflo(bb.w), bfhi(bb.w)}; b0 = b0 * bs; b1 = b1 * bs; }
;                     else { b0 = *(const f32x4*)(base + off); b1 = *(const f32x4*)(base + off + 4); }
;                     const f32x4 o0 = b0 + acc[ai][bj][m][0] * alpha, o1 = b1 + acc[ai][bj][m][1] * alpha;
;                     if (WOUT) { *(f32x4*)(out + off) = o0; *(f32x4*)(out + off + 4) = o1; }
;                     if (WB) { ss += (o0[0] * o0[0] + o0[1] * o0[1]) + (o0[2] * o0[2] + o0[3] * o0[3]) + (o1[0] * o1[0] + o1[1] * o1[1]) + (o1[2] * o1[2] + o1[3] * o1[3]);
;                         u32x4 w; w.x = pk2(o0[0], o0[1]); w.y = pk2(o0[2], o0[3]); w.z = pk2(o1[0], o1[1]); w.w = pk2(o1[2], o1[3]); *(u32x4*)(xb + off) = w; }
;                 }
;                 if (WB) { ss = quad_sum(ss); if (fq == 0) atomic_addf(P + row, ss); }
.LBB0_547:
	s_or_b64 exec, exec, s[12:13]
	v_or_b32_e32 v112, 16, v150
	s_waitcnt lgkmcnt(0)
	v_ashrrev_i32_e32 v113, 31, v112
	v_lshlrev_b64 v[114:115], 10, v[112:113]
	v_lshl_add_u64 v[114:115], v[114:115], 0, v[148:149]
	v_lshlrev_b64 v[122:123], 1, v[114:115]
	v_lshl_add_u64 v[114:115], s[14:15], 0, v[122:123]
	v_lshl_add_u64 v[118:119], v[112:113], 2, s[10:11]
	v_lshl_add_u64 v[126:127], s[34:35], 0, v[122:123]
	v_or_b32_e32 v122, 0x100, v122
	s_nop 0
	s_nop 0
	s_nop 0
	v_lshl_add_u64 v[118:119], s[14:15], 0, v[122:123]
	s_nop 0
	v_lshlrev_b32_e32 v162, 16, v206
	v_and_b32_e32 v163, 0xffff0000, v206
	v_lshlrev_b32_e32 v114, 16, v207
	v_and_b32_e32 v115, 0xffff0000, v207
	v_lshlrev_b32_e32 v164, 16, v208
	v_and_b32_e32 v165, 0xffff0000, v208
	v_lshlrev_b32_e32 v116, 16, v209
	v_and_b32_e32 v117, 0xffff0000, v209
	v_pk_mul_f32 v[162:163], v[232:233], v[162:163] op_sel_hi:[0,1]
	v_lshlrev_b32_e32 v166, 16, v210
	v_and_b32_e32 v167, 0xffff0000, v210
	v_lshlrev_b32_e32 v118, 16, v211
	v_and_b32_e32 v119, 0xffff0000, v211
	v_pk_mul_f32 v[114:115], v[232:233], v[114:115] op_sel_hi:[0,1]
	v_pk_mul_f32 v[164:165], v[232:233], v[164:165] op_sel_hi:[0,1]
	v_pk_mul_f32 v[116:117], v[232:233], v[116:117] op_sel_hi:[0,1]
	v_lshlrev_b32_e32 v168, 16, v212
	v_and_b32_e32 v169, 0xffff0000, v212
	v_lshlrev_b32_e32 v120, 16, v213
	v_and_b32_e32 v121, 0xffff0000, v213
	v_pk_fma_f32 v[108:109], v[108:109], 0.5, v[162:163] op_sel_hi:[1,0,1]
	v_pk_mul_f32 v[162:163], v[232:233], v[166:167] op_sel_hi:[0,1]
	v_pk_mul_f32 v[118:119], v[232:233], v[118:119] op_sel_hi:[0,1]
	v_pk_fma_f32 v[110:111], v[110:111], 0.5, v[114:115] op_sel_hi:[1,0,1]
	v_pk_fma_f32 v[114:115], v[106:107], 0.5, v[116:117] op_sel_hi:[1,0,1]
	v_pk_fma_f32 v[116:117], v[104:105], 0.5, v[164:165] op_sel_hi:[1,0,1]
	v_pk_mul_f32 v[164:165], v[232:233], v[168:169] op_sel_hi:[0,1]
	v_pk_mul_f32 v[120:121], v[232:233], v[120:121] op_sel_hi:[0,1]
	v_pk_fma_f32 v[102:103], v[102:103], 0.5, v[118:119] op_sel_hi:[1,0,1]
	v_pk_fma_f32 v[100:101], v[100:101], 0.5, v[162:163] op_sel_hi:[1,0,1]
	v_mul_f32_e32 v107, v109, v109
	v_mul_f32_e32 v124, v111, v111
	v_pk_fma_f32 v[118:119], v[98:99], 0.5, v[120:121] op_sel_hi:[1,0,1]
	v_pk_fma_f32 v[120:121], v[96:97], 0.5, v[164:165] op_sel_hi:[1,0,1]
	v_mul_f32_e32 v96, v101, v101
	v_mul_f32_e32 v97, v103, v103
	v_mul_f32_e32 v125, v117, v117
	v_fmac_f32_e32 v107, v108, v108
	v_fmac_f32_e32 v124, v110, v110
	v_mul_f32_e32 v98, v121, v121
	v_fmac_f32_e32 v96, v100, v100
	v_fmac_f32_e32 v97, v102, v102
	v_mul_f32_e32 v151, v115, v115
	v_fmac_f32_e32 v125, v116, v116
	v_mul_f32_e32 v99, v119, v119
	v_add_f32_e32 v107, v107, v124
	v_fmac_f32_e32 v98, v120, v120
	v_add_f32_e32 v96, v96, v97
	v_fmac_f32_e32 v151, v114, v114
	v_add_f32_e32 v107, v125, v107
	v_add_f32_e32 v96, v98, v96
	v_fmac_f32_e32 v99, v118, v118
	v_add_f32_e32 v97, v151, v107
	v_add_f32_e32 v96, v99, v96
	v_add_f32_e32 v96, v97, v96
	ds_bpermute_b32 v97, v160, v96
	v_cvt_pk_bf16_f32 v104, v108, v109
	v_cvt_pk_bf16_f32 v105, v110, v111
	v_cvt_pk_bf16_f32 v106, v116, v117
	v_cvt_pk_bf16_f32 v107, v114, v115
	s_waitcnt lgkmcnt(0)
	v_add_f32_e32 v96, v96, v97
	ds_bpermute_b32 v97, v159, v96
	v_cvt_pk_bf16_f32 v98, v100, v101
	v_cvt_pk_bf16_f32 v99, v102, v103
	v_cvt_pk_bf16_f32 v100, v120, v121
	v_cvt_pk_bf16_f32 v101, v118, v119
	v_lshl_add_u64 v[102:103], s[34:35], 0, v[122:123]
	flat_store_dwordx4 v[126:127], v[104:107]
	flat_store_dwordx4 v[102:103], v[98:101]
	s_and_saveexec_b64 s[12:13], s[2:3]
	s_cbranch_execz .LBB0_549
	v_lshl_add_u64 v[98:99], v[112:113], 2, s[42:43]
	s_waitcnt lgkmcnt(0)
	v_add_f32_e32 v96, v96, v97
	global_atomic_add_f32 v[98:99], v96, off
.LBB0_549:
	s_or_b64 exec, exec, s[12:13]
	v_or_b32_e32 v96, 32, v150
	s_waitcnt lgkmcnt(0)
	v_ashrrev_i32_e32 v97, 31, v96
	v_lshlrev_b64 v[98:99], 10, v[96:97]
	v_lshl_add_u64 v[98:99], v[98:99], 0, v[148:149]
	v_lshlrev_b64 v[106:107], 1, v[98:99]
	v_lshl_add_u64 v[98:99], s[14:15], 0, v[106:107]
	v_lshl_add_u64 v[102:103], v[96:97], 2, s[10:11]
	v_lshl_add_u64 v[110:111], s[34:35], 0, v[106:107]
	v_or_b32_e32 v106, 0x100, v106
	s_nop 0
	s_nop 0
	s_nop 0
	v_lshl_add_u64 v[102:103], s[14:15], 0, v[106:107]
	s_nop 0
	v_lshlrev_b32_e32 v112, 16, v214
	v_and_b32_e32 v113, 0xffff0000, v214
	v_lshlrev_b32_e32 v98, 16, v215
	v_and_b32_e32 v99, 0xffff0000, v215
	v_lshlrev_b32_e32 v114, 16, v216
	v_and_b32_e32 v115, 0xffff0000, v216
	v_lshlrev_b32_e32 v100, 16, v217
	v_and_b32_e32 v101, 0xffff0000, v217
	v_pk_mul_f32 v[112:113], v[234:235], v[112:113] op_sel_hi:[0,1]
	v_lshlrev_b32_e32 v116, 16, v218
	v_and_b32_e32 v117, 0xffff0000, v218
	v_lshlrev_b32_e32 v102, 16, v219
	v_and_b32_e32 v103, 0xffff0000, v219
	v_pk_mul_f32 v[98:99], v[234:235], v[98:99] op_sel_hi:[0,1]
	v_pk_mul_f32 v[114:115], v[234:235], v[114:115] op_sel_hi:[0,1]
	v_pk_mul_f32 v[100:101], v[234:235], v[100:101] op_sel_hi:[0,1]
	v_lshlrev_b32_e32 v118, 16, v220
	v_and_b32_e32 v119, 0xffff0000, v220
	v_lshlrev_b32_e32 v104, 16, v221
	v_and_b32_e32 v105, 0xffff0000, v221
	v_pk_fma_f32 v[92:93], v[92:93], 0.5, v[112:113] op_sel_hi:[1,0,1]
	v_pk_mul_f32 v[112:113], v[234:235], v[116:117] op_sel_hi:[0,1]
	v_pk_mul_f32 v[102:103], v[234:235], v[102:103] op_sel_hi:[0,1]
	v_pk_fma_f32 v[94:95], v[94:95], 0.5, v[98:99] op_sel_hi:[1,0,1]
	v_pk_fma_f32 v[98:99], v[90:91], 0.5, v[100:101] op_sel_hi:[1,0,1]
	v_pk_fma_f32 v[100:101], v[88:89], 0.5, v[114:115] op_sel_hi:[1,0,1]
	v_pk_mul_f32 v[114:115], v[234:235], v[118:119] op_sel_hi:[0,1]
	v_pk_mul_f32 v[104:105], v[234:235], v[104:105] op_sel_hi:[0,1]
	v_pk_fma_f32 v[86:87], v[86:87], 0.5, v[102:103] op_sel_hi:[1,0,1]
	v_pk_fma_f32 v[84:85], v[84:85], 0.5, v[112:113] op_sel_hi:[1,0,1]
	v_mul_f32_e32 v91, v93, v93
	v_mul_f32_e32 v108, v95, v95
	v_pk_fma_f32 v[102:103], v[82:83], 0.5, v[104:105] op_sel_hi:[1,0,1]
	v_pk_fma_f32 v[104:105], v[80:81], 0.5, v[114:115] op_sel_hi:[1,0,1]
	v_mul_f32_e32 v80, v85, v85
	v_mul_f32_e32 v81, v87, v87
	v_mul_f32_e32 v109, v101, v101
	v_fmac_f32_e32 v91, v92, v92
	v_fmac_f32_e32 v108, v94, v94
	v_mul_f32_e32 v82, v105, v105
	v_fmac_f32_e32 v80, v84, v84
	v_fmac_f32_e32 v81, v86, v86
	v_mul_f32_e32 v116, v99, v99
	v_fmac_f32_e32 v109, v100, v100
	v_mul_f32_e32 v83, v103, v103
	v_add_f32_e32 v91, v91, v108
	v_fmac_f32_e32 v82, v104, v104
	v_add_f32_e32 v80, v80, v81
	v_fmac_f32_e32 v116, v98, v98
	v_add_f32_e32 v91, v109, v91
	v_add_f32_e32 v80, v82, v80
	v_fmac_f32_e32 v83, v102, v102
	v_add_f32_e32 v81, v116, v91
	v_add_f32_e32 v80, v83, v80
	v_add_f32_e32 v80, v81, v80
	ds_bpermute_b32 v81, v160, v80
	v_cvt_pk_bf16_f32 v88, v92, v93
	v_cvt_pk_bf16_f32 v89, v94, v95
	v_cvt_pk_bf16_f32 v90, v100, v101
	v_cvt_pk_bf16_f32 v91, v98, v99
	s_waitcnt lgkmcnt(0)
; DI unsigned pk2(float lo, float hi) { typedef float v2f __attribute__((ext_vector_type(2))); typedef __bf16 v2b __attribute__((ext_vector_type(2))); v2f v = {lo, hi}; v2b b = __builtin_convertvector(v, v2b); return __builtin_bit_cast(unsigned, b); }
; DI float bflo(unsigned w) { return __uint_as_float(w << 16); }
; DI float bfhi(unsigned w) { return __uint_as_float(w & 0xffff0000u); }
; DI void atomic_addf(float* p, float v) { __builtin_amdgcn_global_atomic_fadd_f32((__attribute__((address_space(1))) float*)p, v); }
; DI float quad_sum(float s) { s += __shfl_xor(s, 16); s += __shfl_xor(s, 32); return s; }
;     DI void operator()(const f32x4 (&acc)[2][2][4][2], const Unit& u, int wr, int wc, int fr, int fq) const {
;     ...
;                 const int row = row0 + ai * 128 + m * 16; float ss = 0.f;
;                 const float bs = (B16 && base) ? base[row] : 1.0f;
; #pragma unroll
;                 for (int bj = 0; bj < 2; ++bj) {
;                     const size_t off = (size_t)row * DM + col0 + bj * 128;
;                     f32x4 b0, b1;
;                     if (B16) { const u32x4 bb = *(const u32x4*)(base16 + off); b0 = (f32x4){bflo(bb.x), bfhi(bb.x), bflo(bb.y), bfhi(bb.y)}; b1 = (f32x4){bflo(bb.z), bfhi(bb.z), bflo(bb.w), bfhi(bb.w)}; b0 = b0 * bs; b1 = b1 * bs; }
;                     else { b0 = *(const f32x4*)(base + off); b1 = *(const f32x4*)(base + off + 4); }
;                     const f32x4 o0 = b0 + acc[ai][bj][m][0] * alpha, o1 = b1 + acc[ai][bj][m][1] * alpha;
;                     if (WOUT) { *(f32x4*)(out + off) = o0; *(f32x4*)(out + off + 4) = o1; }
;                     if (WB) { ss += (o0[0] * o0[0] + o0[1] * o0[1]) + (o0[2] * o0[2] + o0[3] * o0[3]) + (o1[0] * o1[0] + o1[1] * o1[1]) + (o1[2] * o1[2] + o1[3] * o1[3]);
;                         u32x4 w; w.x = pk2(o0[0], o0[1]); w.y = pk2(o0[2], o0[3]); w.z = pk2(o1[0], o1[1]); w.w = pk2(o1[2], o1[3]); *(u32x4*)(xb + off) = w; }
;                 }
;                 if (WB) { ss = quad_sum(ss); if (fq == 0) atomic_addf(P + row, ss); }
	v_add_f32_e32 v80, v80, v81
	ds_bpermute_b32 v81, v159, v80
	v_cvt_pk_bf16_f32 v82, v84, v85
	v_cvt_pk_bf16_f32 v83, v86, v87
	v_cvt_pk_bf16_f32 v84, v104, v105
	v_cvt_pk_bf16_f32 v85, v102, v103
	v_lshl_add_u64 v[86:87], s[34:35], 0, v[106:107]
	flat_store_dwordx4 v[110:111], v[88:91]
	flat_store_dwordx4 v[86:87], v[82:85]
	s_and_saveexec_b64 s[12:13], s[2:3]
	s_cbranch_execz .LBB0_551
	v_lshl_add_u64 v[82:83], v[96:97], 2, s[42:43]
	s_waitcnt lgkmcnt(0)
	v_add_f32_e32 v80, v80, v81
	global_atomic_add_f32 v[82:83], v80, off
.LBB0_551:
	s_or_b64 exec, exec, s[12:13]
	v_or_b32_e32 v80, 48, v150
	s_waitcnt lgkmcnt(0)
	v_ashrrev_i32_e32 v81, 31, v80
	v_lshlrev_b64 v[82:83], 10, v[80:81]
	v_lshl_add_u64 v[82:83], v[82:83], 0, v[148:149]
	v_lshlrev_b64 v[90:91], 1, v[82:83]
	v_lshl_add_u64 v[82:83], s[14:15], 0, v[90:91]
	v_lshl_add_u64 v[86:87], v[80:81], 2, s[10:11]
	v_lshl_add_u64 v[94:95], s[34:35], 0, v[90:91]
	v_or_b32_e32 v90, 0x100, v90
	s_nop 0
	s_nop 0
	s_nop 0
	v_lshl_add_u64 v[86:87], s[14:15], 0, v[90:91]
	s_nop 0
	v_lshlrev_b32_e32 v96, 16, v222
	v_and_b32_e32 v97, 0xffff0000, v222
	v_lshlrev_b32_e32 v82, 16, v223
	v_and_b32_e32 v83, 0xffff0000, v223
	v_lshlrev_b32_e32 v98, 16, v224
	v_and_b32_e32 v99, 0xffff0000, v224
	v_lshlrev_b32_e32 v84, 16, v225
	v_and_b32_e32 v85, 0xffff0000, v225
	v_pk_mul_f32 v[96:97], v[236:237], v[96:97] op_sel_hi:[0,1]
	v_lshlrev_b32_e32 v100, 16, v226
	v_and_b32_e32 v101, 0xffff0000, v226
	v_lshlrev_b32_e32 v86, 16, v227
	v_and_b32_e32 v87, 0xffff0000, v227
	v_pk_mul_f32 v[82:83], v[236:237], v[82:83] op_sel_hi:[0,1]
	v_pk_mul_f32 v[98:99], v[236:237], v[98:99] op_sel_hi:[0,1]
	v_pk_mul_f32 v[84:85], v[236:237], v[84:85] op_sel_hi:[0,1]
	v_lshlrev_b32_e32 v102, 16, v228
	v_and_b32_e32 v103, 0xffff0000, v228
	v_lshlrev_b32_e32 v88, 16, v229
	v_and_b32_e32 v89, 0xffff0000, v229
	v_pk_fma_f32 v[76:77], v[76:77], 0.5, v[96:97] op_sel_hi:[1,0,1]
	v_pk_mul_f32 v[96:97], v[236:237], v[100:101] op_sel_hi:[0,1]
	v_pk_mul_f32 v[86:87], v[236:237], v[86:87] op_sel_hi:[0,1]
	v_pk_fma_f32 v[78:79], v[78:79], 0.5, v[82:83] op_sel_hi:[1,0,1]
	v_pk_fma_f32 v[82:83], v[74:75], 0.5, v[84:85] op_sel_hi:[1,0,1]
	v_pk_fma_f32 v[84:85], v[72:73], 0.5, v[98:99] op_sel_hi:[1,0,1]
	v_pk_mul_f32 v[98:99], v[236:237], v[102:103] op_sel_hi:[0,1]
	v_pk_mul_f32 v[88:89], v[236:237], v[88:89] op_sel_hi:[0,1]
	v_add_u32_e32 v184, 0x40000, v190
	v_mov_b32_e32 v185, v191
	v_lshl_add_u64 v[186:187], s[14:15], 0, v[184:185]
	global_load_dwordx4 v[198:201], v[186:187], off
	global_load_dwordx4 v[202:205], v[186:187], off offset:256
	global_load_dword v230, v[188:189], off offset:512
	v_add_u32_e32 v184, 0x48000, v190
	v_mov_b32_e32 v185, v191
	v_lshl_add_u64 v[186:187], s[14:15], 0, v[184:185]
	global_load_dwordx4 v[206:209], v[186:187], off
	global_load_dwordx4 v[210:213], v[186:187], off offset:256
	global_load_dword v232, v[188:189], off offset:576
	v_add_u32_e32 v184, 0x50000, v190
	v_mov_b32_e32 v185, v191
	v_lshl_add_u64 v[186:187], s[14:15], 0, v[184:185]
	global_load_dwordx4 v[214:217], v[186:187], off
	global_load_dwordx4 v[218:221], v[186:187], off offset:256
	global_load_dword v234, v[188:189], off offset:640
	v_add_u32_e32 v184, 0x58000, v190
	v_mov_b32_e32 v185, v191
	v_lshl_add_u64 v[186:187], s[14:15], 0, v[184:185]
	global_load_dwordx4 v[222:225], v[186:187], off
	global_load_dwordx4 v[226:229], v[186:187], off offset:256
	global_load_dword v236, v[188:189], off offset:704
	v_pk_fma_f32 v[70:71], v[70:71], 0.5, v[86:87] op_sel_hi:[1,0,1]
	v_pk_fma_f32 v[68:69], v[68:69], 0.5, v[96:97] op_sel_hi:[1,0,1]
	v_mul_f32_e32 v75, v77, v77
	v_mul_f32_e32 v92, v79, v79
	v_pk_fma_f32 v[86:87], v[66:67], 0.5, v[88:89] op_sel_hi:[1,0,1]
	v_pk_fma_f32 v[88:89], v[64:65], 0.5, v[98:99] op_sel_hi:[1,0,1]
	v_mul_f32_e32 v64, v69, v69
	v_mul_f32_e32 v65, v71, v71
	v_mul_f32_e32 v93, v85, v85
	v_fmac_f32_e32 v75, v76, v76
	v_fmac_f32_e32 v92, v78, v78
	v_mul_f32_e32 v66, v89, v89
	v_fmac_f32_e32 v64, v68, v68
	v_fmac_f32_e32 v65, v70, v70
	v_mul_f32_e32 v100, v83, v83
	v_fmac_f32_e32 v93, v84, v84
	v_mul_f32_e32 v67, v87, v87
	v_add_f32_e32 v75, v75, v92
	v_fmac_f32_e32 v66, v88, v88
	v_add_f32_e32 v64, v64, v65
	v_fmac_f32_e32 v100, v82, v82
	v_add_f32_e32 v75, v93, v75
	v_add_f32_e32 v64, v66, v64
	v_fmac_f32_e32 v67, v86, v86
	v_add_f32_e32 v65, v100, v75
	v_add_f32_e32 v64, v67, v64
	v_add_f32_e32 v64, v65, v64
	ds_bpermute_b32 v65, v160, v64
	v_cvt_pk_bf16_f32 v72, v76, v77
	v_cvt_pk_bf16_f32 v73, v78, v79
	v_cvt_pk_bf16_f32 v74, v84, v85
	v_cvt_pk_bf16_f32 v75, v82, v83
	s_waitcnt lgkmcnt(0)
	v_add_f32_e32 v64, v64, v65
	ds_bpermute_b32 v65, v159, v64
	v_cvt_pk_bf16_f32 v66, v68, v69
	v_cvt_pk_bf16_f32 v67, v70, v71
	v_cvt_pk_bf16_f32 v68, v88, v89
	v_cvt_pk_bf16_f32 v69, v86, v87
	v_lshl_add_u64 v[70:71], s[34:35], 0, v[90:91]
	flat_store_dwordx4 v[94:95], v[72:75]
	flat_store_dwordx4 v[70:71], v[66:69]
	s_and_saveexec_b64 s[12:13], s[2:3]
	s_cbranch_execz .LBB0_553
	v_lshl_add_u64 v[66:67], v[80:81], 2, s[42:43]
	s_waitcnt lgkmcnt(0)
	v_add_f32_e32 v64, v64, v65
	global_atomic_add_f32 v[66:67], v64, off
; DI unsigned pk2(float lo, float hi) { typedef float v2f __attribute__((ext_vector_type(2))); typedef __bf16 v2b __attribute__((ext_vector_type(2))); v2f v = {lo, hi}; v2b b = __builtin_convertvector(v, v2b); return __builtin_bit_cast(unsigned, b); }
; DI float bflo(unsigned w) { return __uint_as_float(w << 16); }
; DI float bfhi(unsigned w) { return __uint_as_float(w & 0xffff0000u); }
; DI void atomic_addf(float* p, float v) { __builtin_amdgcn_global_atomic_fadd_f32((__attribute__((address_space(1))) float*)p, v); }
; DI float quad_sum(float s) { s += __shfl_xor(s, 16); s += __shfl_xor(s, 32); return s; }
;     DI void operator()(const f32x4 (&acc)[2][2][4][2], const Unit& u, int wr, int wc, int fr, int fq) const {
;     ...
;                 const int row = row0 + ai * 128 + m * 16; float ss = 0.f;
;                 const float bs = (B16 && base) ? base[row] : 1.0f;
; #pragma unroll
;                 for (int bj = 0; bj < 2; ++bj) {
;                     const size_t off = (size_t)row * DM + col0 + bj * 128;
;                     f32x4 b0, b1;
;                     if (B16) { const u32x4 bb = *(const u32x4*)(base16 + off); b0 = (f32x4){bflo(bb.x), bfhi(bb.x), bflo(bb.y), bfhi(bb.y)}; b1 = (f32x4){bflo(bb.z), bfhi(bb.z), bflo(bb.w), bfhi(bb.w)}; b0 = b0 * bs; b1 = b1 * bs; }
;                     else { b0 = *(const f32x4*)(base + off); b1 = *(const f32x4*)(base + off + 4); }
;                     const f32x4 o0 = b0 + acc[ai][bj][m][0] * alpha, o1 = b1 + acc[ai][bj][m][1] * alpha;
;                     if (WOUT) { *(f32x4*)(out + off) = o0; *(f32x4*)(out + off + 4) = o1; }
;                     if (WB) { ss += (o0[0] * o0[0] + o0[1] * o0[1]) + (o0[2] * o0[2] + o0[3] * o0[3]) + (o1[0] * o1[0] + o1[1] * o1[1]) + (o1[2] * o1[2] + o1[3] * o1[3]);
;                         u32x4 w; w.x = pk2(o0[0], o0[1]); w.y = pk2(o0[2], o0[3]); w.z = pk2(o1[0], o1[1]); w.w = pk2(o1[2], o1[3]); *(u32x4*)(xb + off) = w; }
;                 }
;                 if (WB) { ss = quad_sum(ss); if (fq == 0) atomic_addf(P + row, ss); }
.LBB0_553:
	s_or_b64 exec, exec, s[12:13]
	v_add_u32_e32 v64, 0x80, v150
	s_waitcnt lgkmcnt(0)
	v_ashrrev_i32_e32 v65, 31, v64
	v_lshlrev_b64 v[66:67], 10, v[64:65]
	v_lshl_add_u64 v[66:67], v[66:67], 0, v[148:149]
	v_lshlrev_b64 v[74:75], 1, v[66:67]
	v_lshl_add_u64 v[66:67], s[14:15], 0, v[74:75]
	v_lshl_add_u64 v[78:79], s[34:35], 0, v[74:75]
	v_or_b32_e32 v74, 0x100, v74
	v_lshl_add_u64 v[70:71], s[14:15], 0, v[74:75]
	s_nop 0
	s_nop 0
	s_nop 0
	s_waitcnt vmcnt(2)
	v_lshlrev_b32_e32 v80, 16, v198
	s_nop 0
	v_and_b32_e32 v81, 0xffff0000, v198
	v_lshlrev_b32_e32 v66, 16, v199
	v_and_b32_e32 v67, 0xffff0000, v199
	v_lshlrev_b32_e32 v82, 16, v200
	v_and_b32_e32 v83, 0xffff0000, v200
	v_lshlrev_b32_e32 v68, 16, v201
	v_and_b32_e32 v69, 0xffff0000, v201
	v_pk_mul_f32 v[80:81], v[230:231], v[80:81] op_sel_hi:[0,1]
	v_pk_mul_f32 v[66:67], v[230:231], v[66:67] op_sel_hi:[0,1]
	v_pk_mul_f32 v[82:83], v[230:231], v[82:83] op_sel_hi:[0,1]
	v_pk_mul_f32 v[68:69], v[230:231], v[68:69] op_sel_hi:[0,1]
	v_pk_fma_f32 v[60:61], v[60:61], 0.5, v[80:81] op_sel_hi:[1,0,1]
	v_pk_fma_f32 v[62:63], v[62:63], 0.5, v[66:67] op_sel_hi:[1,0,1]
	v_pk_fma_f32 v[66:67], v[58:59], 0.5, v[68:69] op_sel_hi:[1,0,1]
	v_pk_fma_f32 v[68:69], v[56:57], 0.5, v[82:83] op_sel_hi:[1,0,1]
	v_mul_f32_e32 v59, v61, v61
	v_fmac_f32_e32 v59, v60, v60
	v_cvt_pk_bf16_f32 v56, v60, v61
	v_cvt_pk_bf16_f32 v57, v62, v63
	v_cvt_pk_bf16_f32 v58, v68, v69
	v_lshlrev_b32_e32 v84, 16, v202
	v_and_b32_e32 v85, 0xffff0000, v202
	v_lshlrev_b32_e32 v70, 16, v203
	v_and_b32_e32 v71, 0xffff0000, v203
	v_lshlrev_b32_e32 v86, 16, v204
	v_and_b32_e32 v87, 0xffff0000, v204
	v_lshlrev_b32_e32 v72, 16, v205
	v_and_b32_e32 v73, 0xffff0000, v205
	v_pk_mul_f32 v[80:81], v[230:231], v[84:85] op_sel_hi:[0,1]
	v_pk_mul_f32 v[70:71], v[230:231], v[70:71] op_sel_hi:[0,1]
	v_pk_mul_f32 v[82:83], v[230:231], v[86:87] op_sel_hi:[0,1]
	v_pk_mul_f32 v[72:73], v[230:231], v[72:73] op_sel_hi:[0,1]
	v_pk_fma_f32 v[54:55], v[54:55], 0.5, v[70:71] op_sel_hi:[1,0,1]
	v_pk_fma_f32 v[52:53], v[52:53], 0.5, v[80:81] op_sel_hi:[1,0,1]
	v_mul_f32_e32 v76, v63, v63
	v_pk_fma_f32 v[70:71], v[50:51], 0.5, v[72:73] op_sel_hi:[1,0,1]
	v_pk_fma_f32 v[72:73], v[48:49], 0.5, v[82:83] op_sel_hi:[1,0,1]
	v_mul_f32_e32 v48, v53, v53
	v_mul_f32_e32 v49, v55, v55
	v_mul_f32_e32 v77, v69, v69
	v_fmac_f32_e32 v76, v62, v62
	v_mul_f32_e32 v50, v73, v73
	v_fmac_f32_e32 v48, v52, v52
	v_fmac_f32_e32 v49, v54, v54
	v_mul_f32_e32 v84, v67, v67
	v_fmac_f32_e32 v77, v68, v68
	v_mul_f32_e32 v51, v71, v71
	v_add_f32_e32 v59, v59, v76
	v_fmac_f32_e32 v50, v72, v72
	v_add_f32_e32 v48, v48, v49
	v_fmac_f32_e32 v84, v66, v66
	v_add_f32_e32 v59, v77, v59
	v_add_f32_e32 v48, v50, v48
	v_fmac_f32_e32 v51, v70, v70
	v_add_f32_e32 v49, v84, v59
	v_add_f32_e32 v48, v51, v48
	v_add_f32_e32 v48, v49, v48
	ds_bpermute_b32 v49, v160, v48
	v_cvt_pk_bf16_f32 v59, v66, v67
	v_cvt_pk_bf16_f32 v50, v52, v53
	v_cvt_pk_bf16_f32 v51, v54, v55
	v_cvt_pk_bf16_f32 v52, v72, v73
	s_waitcnt lgkmcnt(0)
	v_add_f32_e32 v48, v48, v49
	ds_bpermute_b32 v49, v159, v48
	v_cvt_pk_bf16_f32 v53, v70, v71
	v_lshl_add_u64 v[54:55], s[34:35], 0, v[74:75]
	flat_store_dwordx4 v[78:79], v[56:59]
	flat_store_dwordx4 v[54:55], v[50:53]
	s_and_saveexec_b64 s[12:13], s[2:3]
	s_cbranch_execz .LBB0_555
	v_lshl_add_u64 v[50:51], v[64:65], 2, s[42:43]
	s_waitcnt lgkmcnt(0)
	v_add_f32_e32 v48, v48, v49
	global_atomic_add_f32 v[50:51], v48, off
.LBB0_555:
	s_or_b64 exec, exec, s[12:13]
	v_add_u32_e32 v48, 0x90, v150
	s_waitcnt lgkmcnt(0)
	v_ashrrev_i32_e32 v49, 31, v48
	v_lshlrev_b64 v[50:51], 10, v[48:49]
	v_lshl_add_u64 v[50:51], v[50:51], 0, v[148:149]
	v_lshlrev_b64 v[58:59], 1, v[50:51]
	v_lshl_add_u64 v[50:51], s[14:15], 0, v[58:59]
	v_lshl_add_u64 v[62:63], s[34:35], 0, v[58:59]
	v_or_b32_e32 v58, 0x100, v58
	v_lshl_add_u64 v[54:55], s[14:15], 0, v[58:59]
	s_nop 0
	s_nop 0
	s_nop 0
	v_lshlrev_b32_e32 v64, 16, v206
	s_nop 0
	v_and_b32_e32 v65, 0xffff0000, v206
	v_lshlrev_b32_e32 v50, 16, v207
	v_and_b32_e32 v51, 0xffff0000, v207
	v_lshlrev_b32_e32 v66, 16, v208
	v_and_b32_e32 v67, 0xffff0000, v208
	v_lshlrev_b32_e32 v52, 16, v209
	v_and_b32_e32 v53, 0xffff0000, v209
	v_pk_mul_f32 v[64:65], v[232:233], v[64:65] op_sel_hi:[0,1]
	v_pk_mul_f32 v[50:51], v[232:233], v[50:51] op_sel_hi:[0,1]
	v_pk_mul_f32 v[66:67], v[232:233], v[66:67] op_sel_hi:[0,1]
	v_pk_mul_f32 v[52:53], v[232:233], v[52:53] op_sel_hi:[0,1]
	v_pk_fma_f32 v[44:45], v[44:45], 0.5, v[64:65] op_sel_hi:[1,0,1]
	v_pk_fma_f32 v[46:47], v[46:47], 0.5, v[50:51] op_sel_hi:[1,0,1]
	v_pk_fma_f32 v[50:51], v[42:43], 0.5, v[52:53] op_sel_hi:[1,0,1]
	v_pk_fma_f32 v[52:53], v[40:41], 0.5, v[66:67] op_sel_hi:[1,0,1]
	v_mul_f32_e32 v43, v45, v45
	v_fmac_f32_e32 v43, v44, v44
	v_cvt_pk_bf16_f32 v40, v44, v45
	v_cvt_pk_bf16_f32 v41, v46, v47
	v_cvt_pk_bf16_f32 v42, v52, v53
	v_lshlrev_b32_e32 v68, 16, v210
	v_and_b32_e32 v69, 0xffff0000, v210
	v_lshlrev_b32_e32 v54, 16, v211
	v_and_b32_e32 v55, 0xffff0000, v211
	v_lshlrev_b32_e32 v70, 16, v212
	v_and_b32_e32 v71, 0xffff0000, v212
	v_lshlrev_b32_e32 v56, 16, v213
	v_and_b32_e32 v57, 0xffff0000, v213
	v_pk_mul_f32 v[64:65], v[232:233], v[68:69] op_sel_hi:[0,1]
	v_pk_mul_f32 v[54:55], v[232:233], v[54:55] op_sel_hi:[0,1]
	v_pk_mul_f32 v[66:67], v[232:233], v[70:71] op_sel_hi:[0,1]
	v_pk_mul_f32 v[56:57], v[232:233], v[56:57] op_sel_hi:[0,1]
	v_pk_fma_f32 v[38:39], v[38:39], 0.5, v[54:55] op_sel_hi:[1,0,1]
	v_pk_fma_f32 v[36:37], v[36:37], 0.5, v[64:65] op_sel_hi:[1,0,1]
	v_mul_f32_e32 v60, v47, v47
	v_pk_fma_f32 v[54:55], v[34:35], 0.5, v[56:57] op_sel_hi:[1,0,1]
	v_pk_fma_f32 v[56:57], v[32:33], 0.5, v[66:67] op_sel_hi:[1,0,1]
	v_mul_f32_e32 v32, v37, v37
	v_mul_f32_e32 v33, v39, v39
	v_mul_f32_e32 v61, v53, v53
	v_fmac_f32_e32 v60, v46, v46
	v_mul_f32_e32 v34, v57, v57
	v_fmac_f32_e32 v32, v36, v36
	v_fmac_f32_e32 v33, v38, v38
	v_mul_f32_e32 v68, v51, v51
	v_fmac_f32_e32 v61, v52, v52
	v_mul_f32_e32 v35, v55, v55
	v_add_f32_e32 v43, v43, v60
	v_fmac_f32_e32 v34, v56, v56
	v_add_f32_e32 v32, v32, v33
	v_fmac_f32_e32 v68, v50, v50
	v_add_f32_e32 v43, v61, v43
	v_add_f32_e32 v32, v34, v32
	v_fmac_f32_e32 v35, v54, v54
	v_add_f32_e32 v33, v68, v43
	v_add_f32_e32 v32, v35, v32
	v_add_f32_e32 v32, v33, v32
	ds_bpermute_b32 v33, v160, v32
	v_cvt_pk_bf16_f32 v43, v50, v51
	v_cvt_pk_bf16_f32 v34, v36, v37
	v_cvt_pk_bf16_f32 v35, v38, v39
	v_cvt_pk_bf16_f32 v36, v56, v57
	s_waitcnt lgkmcnt(0)
	v_add_f32_e32 v32, v32, v33
	ds_bpermute_b32 v33, v159, v32
	v_cvt_pk_bf16_f32 v37, v54, v55
	v_lshl_add_u64 v[38:39], s[34:35], 0, v[58:59]
	flat_store_dwordx4 v[62:63], v[40:43]
	flat_store_dwordx4 v[38:39], v[34:37]
	s_and_saveexec_b64 s[12:13], s[2:3]
	s_cbranch_execz .LBB0_557
	v_lshl_add_u64 v[34:35], v[48:49], 2, s[42:43]
	s_waitcnt lgkmcnt(0)
	v_add_f32_e32 v32, v32, v33
	global_atomic_add_f32 v[34:35], v32, off
; DI unsigned pk2(float lo, float hi) { typedef float v2f __attribute__((ext_vector_type(2))); typedef __bf16 v2b __attribute__((ext_vector_type(2))); v2f v = {lo, hi}; v2b b = __builtin_convertvector(v, v2b); return __builtin_bit_cast(unsigned, b); }
; DI float bflo(unsigned w) { return __uint_as_float(w << 16); }
; DI float bfhi(unsigned w) { return __uint_as_float(w & 0xffff0000u); }
; DI void atomic_addf(float* p, float v) { __builtin_amdgcn_global_atomic_fadd_f32((__attribute__((address_space(1))) float*)p, v); }
; DI float quad_sum(float s) { s += __shfl_xor(s, 16); s += __shfl_xor(s, 32); return s; }
;     DI void operator()(const f32x4 (&acc)[2][2][4][2], const Unit& u, int wr, int wc, int fr, int fq) const {
;     ...
;                 const int row = row0 + ai * 128 + m * 16; float ss = 0.f;
;                 const float bs = (B16 && base) ? base[row] : 1.0f;
; #pragma unroll
;                 for (int bj = 0; bj < 2; ++bj) {
;                     const size_t off = (size_t)row * DM + col0 + bj * 128;
;                     f32x4 b0, b1;
;                     if (B16) { const u32x4 bb = *(const u32x4*)(base16 + off); b0 = (f32x4){bflo(bb.x), bfhi(bb.x), bflo(bb.y), bfhi(bb.y)}; b1 = (f32x4){bflo(bb.z), bfhi(bb.z), bflo(bb.w), bfhi(bb.w)}; b0 = b0 * bs; b1 = b1 * bs; }
;                     else { b0 = *(const f32x4*)(base + off); b1 = *(const f32x4*)(base + off + 4); }
;                     const f32x4 o0 = b0 + acc[ai][bj][m][0] * alpha, o1 = b1 + acc[ai][bj][m][1] * alpha;
;                     if (WOUT) { *(f32x4*)(out + off) = o0; *(f32x4*)(out + off + 4) = o1; }
;                     if (WB) { ss += (o0[0] * o0[0] + o0[1] * o0[1]) + (o0[2] * o0[2] + o0[3] * o0[3]) + (o1[0] * o1[0] + o1[1] * o1[1]) + (o1[2] * o1[2] + o1[3] * o1[3]);
;                         u32x4 w; w.x = pk2(o0[0], o0[1]); w.y = pk2(o0[2], o0[3]); w.z = pk2(o1[0], o1[1]); w.w = pk2(o1[2], o1[3]); *(u32x4*)(xb + off) = w; }
;                 }
;                 if (WB) { ss = quad_sum(ss); if (fq == 0) atomic_addf(P + row, ss); }
.LBB0_557:
	s_or_b64 exec, exec, s[12:13]
	v_add_u32_e32 v32, 0xa0, v150
	s_waitcnt lgkmcnt(0)
	v_ashrrev_i32_e32 v33, 31, v32
	v_lshlrev_b64 v[34:35], 10, v[32:33]
	v_lshl_add_u64 v[34:35], v[34:35], 0, v[148:149]
	v_lshlrev_b64 v[42:43], 1, v[34:35]
	v_lshl_add_u64 v[34:35], s[14:15], 0, v[42:43]
	v_lshl_add_u64 v[46:47], s[34:35], 0, v[42:43]
	v_or_b32_e32 v42, 0x100, v42
	v_lshl_add_u64 v[38:39], s[14:15], 0, v[42:43]
	s_nop 0
	s_nop 0
	s_nop 0
	v_lshlrev_b32_e32 v48, 16, v214
	s_nop 0
	v_and_b32_e32 v49, 0xffff0000, v214
	v_lshlrev_b32_e32 v34, 16, v215
	v_and_b32_e32 v35, 0xffff0000, v215
	v_lshlrev_b32_e32 v50, 16, v216
	v_and_b32_e32 v51, 0xffff0000, v216
	v_lshlrev_b32_e32 v36, 16, v217
	v_and_b32_e32 v37, 0xffff0000, v217
	v_pk_mul_f32 v[48:49], v[234:235], v[48:49] op_sel_hi:[0,1]
	v_pk_mul_f32 v[34:35], v[234:235], v[34:35] op_sel_hi:[0,1]
	v_pk_mul_f32 v[50:51], v[234:235], v[50:51] op_sel_hi:[0,1]
	v_pk_mul_f32 v[36:37], v[234:235], v[36:37] op_sel_hi:[0,1]
	v_pk_fma_f32 v[28:29], v[28:29], 0.5, v[48:49] op_sel_hi:[1,0,1]
	v_pk_fma_f32 v[30:31], v[30:31], 0.5, v[34:35] op_sel_hi:[1,0,1]
	v_pk_fma_f32 v[34:35], v[26:27], 0.5, v[36:37] op_sel_hi:[1,0,1]
	v_pk_fma_f32 v[36:37], v[24:25], 0.5, v[50:51] op_sel_hi:[1,0,1]
	v_mul_f32_e32 v27, v29, v29
	v_fmac_f32_e32 v27, v28, v28
	v_cvt_pk_bf16_f32 v24, v28, v29
	v_cvt_pk_bf16_f32 v25, v30, v31
	v_cvt_pk_bf16_f32 v26, v36, v37
	v_lshlrev_b32_e32 v52, 16, v218
	v_and_b32_e32 v53, 0xffff0000, v218
	v_lshlrev_b32_e32 v38, 16, v219
	v_and_b32_e32 v39, 0xffff0000, v219
	v_lshlrev_b32_e32 v54, 16, v220
	v_and_b32_e32 v55, 0xffff0000, v220
	v_lshlrev_b32_e32 v40, 16, v221
	v_and_b32_e32 v41, 0xffff0000, v221
	v_pk_mul_f32 v[48:49], v[234:235], v[52:53] op_sel_hi:[0,1]
	v_pk_mul_f32 v[38:39], v[234:235], v[38:39] op_sel_hi:[0,1]
	v_pk_mul_f32 v[50:51], v[234:235], v[54:55] op_sel_hi:[0,1]
	v_pk_mul_f32 v[40:41], v[234:235], v[40:41] op_sel_hi:[0,1]
	v_pk_fma_f32 v[22:23], v[22:23], 0.5, v[38:39] op_sel_hi:[1,0,1]
	v_pk_fma_f32 v[20:21], v[20:21], 0.5, v[48:49] op_sel_hi:[1,0,1]
	v_mul_f32_e32 v44, v31, v31
	v_pk_fma_f32 v[38:39], v[18:19], 0.5, v[40:41] op_sel_hi:[1,0,1]
	v_pk_fma_f32 v[40:41], v[16:17], 0.5, v[50:51] op_sel_hi:[1,0,1]
	v_mul_f32_e32 v16, v21, v21
	v_mul_f32_e32 v17, v23, v23
	v_mul_f32_e32 v45, v37, v37
	v_fmac_f32_e32 v44, v30, v30
	v_mul_f32_e32 v18, v41, v41
	v_fmac_f32_e32 v16, v20, v20
	v_fmac_f32_e32 v17, v22, v22
	v_mul_f32_e32 v52, v35, v35
	v_fmac_f32_e32 v45, v36, v36
	v_mul_f32_e32 v19, v39, v39
	v_add_f32_e32 v27, v27, v44
	v_fmac_f32_e32 v18, v40, v40
	v_add_f32_e32 v16, v16, v17
	v_fmac_f32_e32 v52, v34, v34
	v_add_f32_e32 v27, v45, v27
	v_add_f32_e32 v16, v18, v16
	v_fmac_f32_e32 v19, v38, v38
	v_add_f32_e32 v17, v52, v27
	v_add_f32_e32 v16, v19, v16
	v_add_f32_e32 v16, v17, v16
	ds_bpermute_b32 v17, v160, v16
	v_cvt_pk_bf16_f32 v27, v34, v35
	v_cvt_pk_bf16_f32 v18, v20, v21
	v_cvt_pk_bf16_f32 v19, v22, v23
	v_cvt_pk_bf16_f32 v20, v40, v41
	s_waitcnt lgkmcnt(0)
	v_add_f32_e32 v16, v16, v17
	ds_bpermute_b32 v17, v159, v16
	v_cvt_pk_bf16_f32 v21, v38, v39
	v_lshl_add_u64 v[22:23], s[34:35], 0, v[42:43]
	flat_store_dwordx4 v[46:47], v[24:27]
	flat_store_dwordx4 v[22:23], v[18:21]
	s_and_saveexec_b64 s[12:13], s[2:3]
	s_cbranch_execz .LBB0_559
	v_lshl_add_u64 v[18:19], v[32:33], 2, s[42:43]
	s_waitcnt lgkmcnt(0)
	v_add_f32_e32 v16, v16, v17
	global_atomic_add_f32 v[18:19], v16, off
.LBB0_559:
	s_or_b64 exec, exec, s[12:13]
	v_add_u32_e32 v16, 0xb0, v150
	s_waitcnt lgkmcnt(0)
	v_ashrrev_i32_e32 v17, 31, v16
	v_lshlrev_b64 v[18:19], 10, v[16:17]
	v_lshl_add_u64 v[18:19], v[18:19], 0, v[148:149]
	v_lshlrev_b64 v[26:27], 1, v[18:19]
	v_lshl_add_u64 v[18:19], s[14:15], 0, v[26:27]
	v_lshl_add_u64 v[30:31], s[34:35], 0, v[26:27]
	v_or_b32_e32 v26, 0x100, v26
	v_lshl_add_u64 v[22:23], s[14:15], 0, v[26:27]
	s_nop 0
	s_nop 0
	s_nop 0
	v_lshlrev_b32_e32 v32, 16, v222
	s_nop 0
	v_and_b32_e32 v33, 0xffff0000, v222
	v_lshlrev_b32_e32 v18, 16, v223
	v_and_b32_e32 v19, 0xffff0000, v223
	v_lshlrev_b32_e32 v34, 16, v224
	v_and_b32_e32 v35, 0xffff0000, v224
	v_lshlrev_b32_e32 v20, 16, v225
	v_and_b32_e32 v21, 0xffff0000, v225
	v_pk_mul_f32 v[32:33], v[236:237], v[32:33] op_sel_hi:[0,1]
	v_pk_mul_f32 v[18:19], v[236:237], v[18:19] op_sel_hi:[0,1]
	v_pk_mul_f32 v[34:35], v[236:237], v[34:35] op_sel_hi:[0,1]
	v_pk_mul_f32 v[20:21], v[236:237], v[20:21] op_sel_hi:[0,1]
	v_pk_fma_f32 v[12:13], v[12:13], 0.5, v[32:33] op_sel_hi:[1,0,1]
	v_pk_fma_f32 v[14:15], v[14:15], 0.5, v[18:19] op_sel_hi:[1,0,1]
	v_pk_fma_f32 v[18:19], v[10:11], 0.5, v[20:21] op_sel_hi:[1,0,1]
	v_pk_fma_f32 v[20:21], v[8:9], 0.5, v[34:35] op_sel_hi:[1,0,1]
	v_mul_f32_e32 v11, v13, v13
	v_fmac_f32_e32 v11, v12, v12
	v_cvt_pk_bf16_f32 v8, v12, v13
	v_cvt_pk_bf16_f32 v9, v14, v15
	v_cvt_pk_bf16_f32 v10, v20, v21
	v_lshlrev_b32_e32 v36, 16, v226
	v_and_b32_e32 v37, 0xffff0000, v226
	v_lshlrev_b32_e32 v22, 16, v227
	v_and_b32_e32 v23, 0xffff0000, v227
	v_lshlrev_b32_e32 v38, 16, v228
	v_and_b32_e32 v39, 0xffff0000, v228
	v_lshlrev_b32_e32 v24, 16, v229
	v_and_b32_e32 v25, 0xffff0000, v229
	v_pk_mul_f32 v[32:33], v[236:237], v[36:37] op_sel_hi:[0,1]
	v_pk_mul_f32 v[22:23], v[236:237], v[22:23] op_sel_hi:[0,1]
	v_pk_mul_f32 v[34:35], v[236:237], v[38:39] op_sel_hi:[0,1]
	v_pk_mul_f32 v[24:25], v[236:237], v[24:25] op_sel_hi:[0,1]
	v_pk_fma_f32 v[6:7], v[6:7], 0.5, v[22:23] op_sel_hi:[1,0,1]
	v_pk_fma_f32 v[4:5], v[4:5], 0.5, v[32:33] op_sel_hi:[1,0,1]
	v_mul_f32_e32 v28, v15, v15
	v_pk_fma_f32 v[22:23], v[2:3], 0.5, v[24:25] op_sel_hi:[1,0,1]
	v_pk_fma_f32 v[24:25], v[0:1], 0.5, v[34:35] op_sel_hi:[1,0,1]
	v_mul_f32_e32 v0, v5, v5
	v_mul_f32_e32 v1, v7, v7
	v_mul_f32_e32 v29, v21, v21
	v_fmac_f32_e32 v28, v14, v14
	v_mul_f32_e32 v2, v25, v25
	v_fmac_f32_e32 v0, v4, v4
	v_fmac_f32_e32 v1, v6, v6
	v_mul_f32_e32 v36, v19, v19
	v_fmac_f32_e32 v29, v20, v20
	v_mul_f32_e32 v3, v23, v23
	v_add_f32_e32 v11, v11, v28
	v_fmac_f32_e32 v2, v24, v24
	v_add_f32_e32 v0, v0, v1
	v_fmac_f32_e32 v36, v18, v18
	v_add_f32_e32 v11, v29, v11
	v_add_f32_e32 v0, v2, v0
	v_fmac_f32_e32 v3, v22, v22
	v_add_f32_e32 v1, v36, v11
	v_add_f32_e32 v0, v3, v0
	v_add_f32_e32 v0, v1, v0
	ds_bpermute_b32 v1, v160, v0
	v_cvt_pk_bf16_f32 v11, v18, v19
	v_cvt_pk_bf16_f32 v2, v4, v5
	v_cvt_pk_bf16_f32 v3, v6, v7
	v_cvt_pk_bf16_f32 v4, v24, v25
	s_waitcnt lgkmcnt(0)
	v_add_f32_e32 v0, v0, v1
	ds_bpermute_b32 v1, v159, v0
	v_cvt_pk_bf16_f32 v5, v22, v23
	v_lshl_add_u64 v[6:7], s[34:35], 0, v[26:27]
	flat_store_dwordx4 v[30:31], v[8:11]
	flat_store_dwordx4 v[6:7], v[2:5]
	s_and_saveexec_b64 s[12:13], s[2:3]
	s_cbranch_execz .LBB0_561
	v_lshl_add_u64 v[2:3], v[16:17], 2, s[42:43]
	s_waitcnt lgkmcnt(0)
	v_add_f32_e32 v0, v0, v1
	global_atomic_add_f32 v[2:3], v0, off

; DI unsigned pk2(float lo, float hi) { typedef float v2f __attribute__((ext_vector_type(2))); typedef __bf16 v2b __attribute__((ext_vector_type(2))); v2f v = {lo, hi}; v2b b = __builtin_convertvector(v, v2b); return __builtin_bit_cast(unsigned, b); }
; DI float bflo(unsigned w) { return __uint_as_float(w << 16); }
; DI float bfhi(unsigned w) { return __uint_as_float(w & 0xffff0000u); }
; DI void atomic_addf(float* p, float v) { __builtin_amdgcn_global_atomic_fadd_f32((__attribute__((address_space(1))) float*)p, v); }
; DI float quad_sum(float s) { s += __shfl_xor(s, 16); s += __shfl_xor(s, 32); return s; }
;     DI void operator()(const f32x4 (&acc)[2][2][4][2], const Unit& u, int wr, int wc, int fr, int fq) const {
;     ...
;                 const int row = row0 + ai * 128 + m * 16; float ss = 0.f;
;                 const float bs = (B16 && base) ? base[row] : 1.0f;
; #pragma unroll
;                 for (int bj = 0; bj < 2; ++bj) {
;                     const size_t off = (size_t)row * DM + col0 + bj * 128;
;                     f32x4 b0, b1;
;                     if (B16) { const u32x4 bb = *(const u32x4*)(base16 + off); b0 = (f32x4){bflo(bb.x), bfhi(bb.x), bflo(bb.y), bfhi(bb.y)}; b1 = (f32x4){bflo(bb.z), bfhi(bb.z), bflo(bb.w), bfhi(bb.w)}; b0 = b0 * bs; b1 = b1 * bs; }
;                     else { b0 = *(const f32x4*)(base + off); b1 = *(const f32x4*)(base + off + 4); }
;                     const f32x4 o0 = b0 + acc[ai][bj][m][0] * alpha, o1 = b1 + acc[ai][bj][m][1] * alpha;
;                     if (WOUT) { *(f32x4*)(out + off) = o0; *(f32x4*)(out + off + 4) = o1; }
;                     if (WB) { ss += (o0[0] * o0[0] + o0[1] * o0[1]) + (o0[2] * o0[2] + o0[3] * o0[3]) + (o1[0] * o1[0] + o1[1] * o1[1]) + (o1[2] * o1[2] + o1[3] * o1[3]);
;                         u32x4 w; w.x = pk2(o0[0], o0[1]); w.y = pk2(o0[2], o0[3]); w.z = pk2(o1[0], o1[1]); w.w = pk2(o1[2], o1[3]); *(u32x4*)(xb + off) = w; }
;                 }
;                 if (WB) { ss = quad_sum(ss); if (fq == 0) atomic_addf(P + row, ss); }
.LBB0_1739:
	v_lshl_add_u32 v146, s36, 8, v148
	v_lshl_or_b32 v144, s34, 8, v150
	v_ashrrev_i32_e32 v147, 31, v146
	v_ashrrev_i32_e32 v145, 31, v144
	v_lshlrev_b64 v[156:157], 10, v[146:147]
	v_lshl_add_u64 v[156:157], v[156:157], 0, v[144:145]
	v_lshlrev_b64 v[166:167], 1, v[156:157]
	v_lshl_add_u64 v[156:157], s[8:9], 0, v[166:167]
	v_lshl_add_u64 v[168:169], s[10:11], 0, v[166:167]
	v_mov_b32_e32 v190, v166
	v_mov_b32_e32 v191, v167
	v_mov_b32_e32 v184, v190
	v_mov_b32_e32 v185, v191
	v_lshl_add_u64 v[186:187], s[8:9], 0, v[184:185]
	global_load_dwordx4 v[198:201], v[186:187], off
	global_load_dwordx4 v[202:205], v[186:187], off offset:256
	v_add_u32_e32 v184, 0x8000, v190
	v_mov_b32_e32 v185, v191
	v_lshl_add_u64 v[186:187], s[8:9], 0, v[184:185]
	global_load_dwordx4 v[206:209], v[186:187], off
	global_load_dwordx4 v[210:213], v[186:187], off offset:256
	v_add_u32_e32 v184, 0x10000, v190
	v_mov_b32_e32 v185, v191
	v_lshl_add_u64 v[186:187], s[8:9], 0, v[184:185]
	global_load_dwordx4 v[214:217], v[186:187], off
	global_load_dwordx4 v[218:221], v[186:187], off offset:256
	v_add_u32_e32 v184, 0x18000, v190
	v_mov_b32_e32 v185, v191
	v_lshl_add_u64 v[186:187], s[8:9], 0, v[184:185]
	global_load_dwordx4 v[222:225], v[186:187], off
	global_load_dwordx4 v[226:229], v[186:187], off offset:256
	v_or_b32_e32 v166, 0x100, v166
	s_nop 0
	v_lshl_add_u64 v[156:157], s[8:9], 0, v[166:167]
	s_nop 0
	v_and_b32_e32 v156, 64, v154
	v_xor_b32_e32 v155, 16, v154
	v_add_u32_e32 v156, 64, v156
	v_xor_b32_e32 v157, 32, v154
	v_cmp_lt_i32_e32 vcc, v155, v156
	s_waitcnt vmcnt(0)
	v_lshlrev_b32_e32 v170, 16, v198
	v_and_b32_e32 v171, 0xffff0000, v198
	v_cndmask_b32_e32 v155, v154, v155, vcc
	v_cmp_lt_i32_e32 vcc, v157, v156
	v_lshlrev_b32_e32 v158, 16, v199
	v_and_b32_e32 v159, 0xffff0000, v199
	v_lshlrev_b32_e32 v172, 16, v200
	v_and_b32_e32 v173, 0xffff0000, v200
	v_lshlrev_b32_e32 v160, 16, v201
	v_and_b32_e32 v161, 0xffff0000, v201
	v_pk_add_f32 v[124:125], v[124:125], v[170:171]
	v_lshlrev_b32_e32 v170, 16, v202
	v_and_b32_e32 v171, 0xffff0000, v202
	v_lshlrev_b32_e32 v162, 16, v203
	v_and_b32_e32 v163, 0xffff0000, v203
	v_cndmask_b32_e32 v157, v154, v157, vcc
	v_pk_add_f32 v[126:127], v[126:127], v[158:159]
	v_pk_add_f32 v[158:159], v[122:123], v[160:161]
	v_pk_add_f32 v[160:161], v[120:121], v[172:173]
	v_lshlrev_b32_e32 v172, 16, v204
	v_and_b32_e32 v173, 0xffff0000, v204
	v_lshlrev_b32_e32 v164, 16, v205
	v_and_b32_e32 v165, 0xffff0000, v205
	v_pk_add_f32 v[118:119], v[118:119], v[162:163]
	v_pk_add_f32 v[116:117], v[116:117], v[170:171]
	v_lshlrev_b32_e32 v156, 2, v155
	v_lshlrev_b32_e32 v155, 2, v157
	v_mul_f32_e32 v123, v125, v125
	v_mul_f32_e32 v157, v127, v127
	v_pk_add_f32 v[162:163], v[114:115], v[164:165]
	v_pk_add_f32 v[164:165], v[112:113], v[172:173]
	v_mul_f32_e32 v112, v117, v117
	v_mul_f32_e32 v113, v119, v119
	v_mul_f32_e32 v174, v161, v161
	v_fmac_f32_e32 v123, v124, v124
	v_fmac_f32_e32 v157, v126, v126
	v_mul_f32_e32 v114, v165, v165
	v_fmac_f32_e32 v112, v116, v116
	v_fmac_f32_e32 v113, v118, v118
	v_mul_f32_e32 v175, v159, v159
	v_fmac_f32_e32 v174, v160, v160
	v_mul_f32_e32 v115, v163, v163
	v_add_f32_e32 v123, v123, v157
	v_fmac_f32_e32 v114, v164, v164
	v_add_f32_e32 v112, v112, v113
	v_fmac_f32_e32 v175, v158, v158
	v_add_f32_e32 v123, v174, v123
	v_add_f32_e32 v112, v114, v112
	v_fmac_f32_e32 v115, v162, v162
	v_add_f32_e32 v113, v175, v123
	v_add_f32_e32 v112, v115, v112
	v_add_f32_e32 v112, v113, v112
	ds_bpermute_b32 v113, v156, v112
	v_cvt_pk_bf16_f32 v120, v124, v125
	v_cvt_pk_bf16_f32 v121, v126, v127
	v_cvt_pk_bf16_f32 v122, v160, v161
	v_cvt_pk_bf16_f32 v123, v158, v159
	s_waitcnt lgkmcnt(0)
	v_add_f32_e32 v112, v112, v113
	ds_bpermute_b32 v113, v155, v112
	v_cvt_pk_bf16_f32 v114, v116, v117
	v_cvt_pk_bf16_f32 v115, v118, v119
	v_cvt_pk_bf16_f32 v116, v164, v165
	v_cvt_pk_bf16_f32 v117, v162, v163
	v_lshl_add_u64 v[118:119], s[10:11], 0, v[166:167]
	flat_store_dwordx4 v[168:169], v[120:123]
	flat_store_dwordx4 v[118:119], v[114:117]
	s_and_saveexec_b64 s[12:13], s[2:3]
	s_cbranch_execz .LBB0_1741
	v_lshl_add_u64 v[114:115], v[146:147], 2, s[14:15]
	s_waitcnt lgkmcnt(0)
	v_add_f32_e32 v112, v112, v113
	global_atomic_add_f32 v[114:115], v112, off
; DI unsigned pk2(float lo, float hi) { typedef float v2f __attribute__((ext_vector_type(2))); typedef __bf16 v2b __attribute__((ext_vector_type(2))); v2f v = {lo, hi}; v2b b = __builtin_convertvector(v, v2b); return __builtin_bit_cast(unsigned, b); }
; DI float bflo(unsigned w) { return __uint_as_float(w << 16); }
; DI float bfhi(unsigned w) { return __uint_as_float(w & 0xffff0000u); }
; DI void atomic_addf(float* p, float v) { __builtin_amdgcn_global_atomic_fadd_f32((__attribute__((address_space(1))) float*)p, v); }
; DI float quad_sum(float s) { s += __shfl_xor(s, 16); s += __shfl_xor(s, 32); return s; }
;     DI void operator()(const f32x4 (&acc)[2][2][4][2], const Unit& u, int wr, int wc, int fr, int fq) const {
;     ...
;                 const int row = row0 + ai * 128 + m * 16; float ss = 0.f;
;                 const float bs = (B16 && base) ? base[row] : 1.0f;
; #pragma unroll
;                 for (int bj = 0; bj < 2; ++bj) {
;                     const size_t off = (size_t)row * DM + col0 + bj * 128;
;                     f32x4 b0, b1;
;                     if (B16) { const u32x4 bb = *(const u32x4*)(base16 + off); b0 = (f32x4){bflo(bb.x), bfhi(bb.x), bflo(bb.y), bfhi(bb.y)}; b1 = (f32x4){bflo(bb.z), bfhi(bb.z), bflo(bb.w), bfhi(bb.w)}; b0 = b0 * bs; b1 = b1 * bs; }
;                     else { b0 = *(const f32x4*)(base + off); b1 = *(const f32x4*)(base + off + 4); }
;                     const f32x4 o0 = b0 + acc[ai][bj][m][0] * alpha, o1 = b1 + acc[ai][bj][m][1] * alpha;
;                     if (WOUT) { *(f32x4*)(out + off) = o0; *(f32x4*)(out + off + 4) = o1; }
;                     if (WB) { ss += (o0[0] * o0[0] + o0[1] * o0[1]) + (o0[2] * o0[2] + o0[3] * o0[3]) + (o1[0] * o1[0] + o1[1] * o1[1]) + (o1[2] * o1[2] + o1[3] * o1[3]);
;                         u32x4 w; w.x = pk2(o0[0], o0[1]); w.y = pk2(o0[2], o0[3]); w.z = pk2(o1[0], o1[1]); w.w = pk2(o1[2], o1[3]); *(u32x4*)(xb + off) = w; }
;                 }
;                 if (WB) { ss = quad_sum(ss); if (fq == 0) atomic_addf(P + row, ss); }
.LBB0_1741:
	s_or_b64 exec, exec, s[12:13]
	v_or_b32_e32 v112, 16, v146
	s_waitcnt lgkmcnt(0)
	v_ashrrev_i32_e32 v113, 31, v112
	v_lshlrev_b64 v[114:115], 10, v[112:113]
	v_lshl_add_u64 v[114:115], v[114:115], 0, v[144:145]
	v_lshlrev_b64 v[122:123], 1, v[114:115]
	v_lshl_add_u64 v[114:115], s[8:9], 0, v[122:123]
	v_lshl_add_u64 v[124:125], s[10:11], 0, v[122:123]
	v_or_b32_e32 v122, 0x100, v122
	s_nop 0
	v_lshl_add_u64 v[118:119], s[8:9], 0, v[122:123]
	s_nop 0
	v_lshlrev_b32_e32 v126, 16, v206
	v_and_b32_e32 v127, 0xffff0000, v206
	v_lshlrev_b32_e32 v114, 16, v207
	v_and_b32_e32 v115, 0xffff0000, v207
	v_lshlrev_b32_e32 v158, 16, v208
	v_and_b32_e32 v159, 0xffff0000, v208
	v_lshlrev_b32_e32 v116, 16, v209
	v_and_b32_e32 v117, 0xffff0000, v209
	v_pk_add_f32 v[108:109], v[108:109], v[126:127]
	v_lshlrev_b32_e32 v126, 16, v210
	v_and_b32_e32 v127, 0xffff0000, v210
	v_lshlrev_b32_e32 v118, 16, v211
	v_and_b32_e32 v119, 0xffff0000, v211
	v_pk_add_f32 v[110:111], v[110:111], v[114:115]
	v_pk_add_f32 v[114:115], v[106:107], v[116:117]
	v_pk_add_f32 v[116:117], v[104:105], v[158:159]
	v_lshlrev_b32_e32 v158, 16, v212
	v_and_b32_e32 v159, 0xffff0000, v212
	v_lshlrev_b32_e32 v120, 16, v213
	v_and_b32_e32 v121, 0xffff0000, v213
	v_pk_add_f32 v[102:103], v[102:103], v[118:119]
	v_pk_add_f32 v[100:101], v[100:101], v[126:127]
	v_mul_f32_e32 v107, v109, v109
	v_mul_f32_e32 v147, v111, v111
	v_pk_add_f32 v[118:119], v[98:99], v[120:121]
	v_pk_add_f32 v[120:121], v[96:97], v[158:159]
	v_mul_f32_e32 v96, v101, v101
	v_mul_f32_e32 v97, v103, v103
	v_mul_f32_e32 v157, v117, v117
	v_fmac_f32_e32 v107, v108, v108
	v_fmac_f32_e32 v147, v110, v110
	v_mul_f32_e32 v98, v121, v121
	v_fmac_f32_e32 v96, v100, v100
	v_fmac_f32_e32 v97, v102, v102
	v_mul_f32_e32 v160, v115, v115
	v_fmac_f32_e32 v157, v116, v116
	v_mul_f32_e32 v99, v119, v119
	v_add_f32_e32 v107, v107, v147
	v_fmac_f32_e32 v98, v120, v120
	v_add_f32_e32 v96, v96, v97
	v_fmac_f32_e32 v160, v114, v114
	v_add_f32_e32 v107, v157, v107
	v_add_f32_e32 v96, v98, v96
	v_fmac_f32_e32 v99, v118, v118
	v_add_f32_e32 v97, v160, v107
	v_add_f32_e32 v96, v99, v96
	v_add_f32_e32 v96, v97, v96
	ds_bpermute_b32 v97, v156, v96
	v_cvt_pk_bf16_f32 v104, v108, v109
	v_cvt_pk_bf16_f32 v105, v110, v111
	v_cvt_pk_bf16_f32 v106, v116, v117
	v_cvt_pk_bf16_f32 v107, v114, v115
	s_waitcnt lgkmcnt(0)
	v_add_f32_e32 v96, v96, v97
	ds_bpermute_b32 v97, v155, v96
	v_cvt_pk_bf16_f32 v98, v100, v101
	v_cvt_pk_bf16_f32 v99, v102, v103
	v_cvt_pk_bf16_f32 v100, v120, v121
	v_cvt_pk_bf16_f32 v101, v118, v119
	v_lshl_add_u64 v[102:103], s[10:11], 0, v[122:123]
	flat_store_dwordx4 v[124:125], v[104:107]
	flat_store_dwordx4 v[102:103], v[98:101]
	s_and_saveexec_b64 s[12:13], s[2:3]
	s_cbranch_execz .LBB0_1743
	v_lshl_add_u64 v[98:99], v[112:113], 2, s[14:15]
	s_waitcnt lgkmcnt(0)
	v_add_f32_e32 v96, v96, v97
	global_atomic_add_f32 v[98:99], v96, off
.LBB0_1743:
	s_or_b64 exec, exec, s[12:13]
	v_or_b32_e32 v96, 32, v146
	s_waitcnt lgkmcnt(0)
	v_ashrrev_i32_e32 v97, 31, v96
	v_lshlrev_b64 v[98:99], 10, v[96:97]
	v_lshl_add_u64 v[98:99], v[98:99], 0, v[144:145]
	v_lshlrev_b64 v[106:107], 1, v[98:99]
	v_lshl_add_u64 v[98:99], s[8:9], 0, v[106:107]
	v_lshl_add_u64 v[108:109], s[10:11], 0, v[106:107]
	v_or_b32_e32 v106, 0x100, v106
	s_nop 0
	v_lshl_add_u64 v[102:103], s[8:9], 0, v[106:107]
	s_nop 0
	v_lshlrev_b32_e32 v110, 16, v214
	v_and_b32_e32 v111, 0xffff0000, v214
	v_lshlrev_b32_e32 v98, 16, v215
	v_and_b32_e32 v99, 0xffff0000, v215
	v_lshlrev_b32_e32 v112, 16, v216
	v_and_b32_e32 v113, 0xffff0000, v216
	v_lshlrev_b32_e32 v100, 16, v217
	v_and_b32_e32 v101, 0xffff0000, v217
	v_pk_add_f32 v[92:93], v[92:93], v[110:111]
	v_lshlrev_b32_e32 v110, 16, v218
	v_and_b32_e32 v111, 0xffff0000, v218
	v_lshlrev_b32_e32 v102, 16, v219
	v_and_b32_e32 v103, 0xffff0000, v219
	v_pk_add_f32 v[94:95], v[94:95], v[98:99]
	v_pk_add_f32 v[98:99], v[90:91], v[100:101]
	v_pk_add_f32 v[100:101], v[88:89], v[112:113]
	v_lshlrev_b32_e32 v112, 16, v220
	v_and_b32_e32 v113, 0xffff0000, v220
	v_lshlrev_b32_e32 v104, 16, v221
	v_and_b32_e32 v105, 0xffff0000, v221
	v_pk_add_f32 v[86:87], v[86:87], v[102:103]
	v_pk_add_f32 v[84:85], v[84:85], v[110:111]
	v_mul_f32_e32 v91, v93, v93
	v_mul_f32_e32 v114, v95, v95
	v_pk_add_f32 v[102:103], v[82:83], v[104:105]
	v_pk_add_f32 v[104:105], v[80:81], v[112:113]
	v_mul_f32_e32 v80, v85, v85
	v_mul_f32_e32 v81, v87, v87
	v_mul_f32_e32 v115, v101, v101
	v_fmac_f32_e32 v91, v92, v92
	v_fmac_f32_e32 v114, v94, v94
	v_mul_f32_e32 v82, v105, v105
	v_fmac_f32_e32 v80, v84, v84
	v_fmac_f32_e32 v81, v86, v86
	v_mul_f32_e32 v116, v99, v99
	v_fmac_f32_e32 v115, v100, v100
	v_mul_f32_e32 v83, v103, v103
	v_add_f32_e32 v91, v91, v114
	v_fmac_f32_e32 v82, v104, v104
	v_add_f32_e32 v80, v80, v81
	v_fmac_f32_e32 v116, v98, v98
	v_add_f32_e32 v91, v115, v91
	v_add_f32_e32 v80, v82, v80
	v_fmac_f32_e32 v83, v102, v102
	v_add_f32_e32 v81, v116, v91
	v_add_f32_e32 v80, v83, v80
	v_add_f32_e32 v80, v81, v80
	ds_bpermute_b32 v81, v156, v80
	v_cvt_pk_bf16_f32 v88, v92, v93
	v_cvt_pk_bf16_f32 v89, v94, v95
	v_cvt_pk_bf16_f32 v90, v100, v101
	v_cvt_pk_bf16_f32 v91, v98, v99
	s_waitcnt lgkmcnt(0)
	v_add_f32_e32 v80, v80, v81
	ds_bpermute_b32 v81, v155, v80
	v_cvt_pk_bf16_f32 v82, v84, v85
	v_cvt_pk_bf16_f32 v83, v86, v87
	v_cvt_pk_bf16_f32 v84, v104, v105
	v_cvt_pk_bf16_f32 v85, v102, v103
	v_lshl_add_u64 v[86:87], s[10:11], 0, v[106:107]
	flat_store_dwordx4 v[108:109], v[88:91]
	flat_store_dwordx4 v[86:87], v[82:85]
	s_and_saveexec_b64 s[12:13], s[2:3]
	v_readlane_b32 s56, v249, 1
	v_readlane_b32 s68, v249, 13
	v_readlane_b32 s69, v249, 14
	v_readlane_b32 s70, v249, 15
	v_readlane_b32 s71, v249, 16
	s_mov_b64 s[28:29], s[68:69]
	s_mov_b64 s[30:31], s[70:71]
	v_readlane_b32 s57, v249, 2
	v_readlane_b32 s58, v249, 3
	v_readlane_b32 s59, v249, 4
	v_readlane_b32 s60, v249, 5
	v_readlane_b32 s61, v249, 6
	v_readlane_b32 s62, v249, 7
	v_readlane_b32 s63, v249, 8
	v_readlane_b32 s64, v249, 9
	v_readlane_b32 s65, v249, 10
	v_readlane_b32 s66, v249, 11
	v_readlane_b32 s67, v249, 12
	s_cbranch_execz .LBB0_1745
	v_lshl_add_u64 v[82:83], v[96:97], 2, s[14:15]
	s_waitcnt lgkmcnt(0)
	v_add_f32_e32 v80, v80, v81
	global_atomic_add_f32 v[82:83], v80, off
; DI unsigned pk2(float lo, float hi) { typedef float v2f __attribute__((ext_vector_type(2))); typedef __bf16 v2b __attribute__((ext_vector_type(2))); v2f v = {lo, hi}; v2b b = __builtin_convertvector(v, v2b); return __builtin_bit_cast(unsigned, b); }
; DI float bflo(unsigned w) { return __uint_as_float(w << 16); }
; DI float bfhi(unsigned w) { return __uint_as_float(w & 0xffff0000u); }
; DI void atomic_addf(float* p, float v) { __builtin_amdgcn_global_atomic_fadd_f32((__attribute__((address_space(1))) float*)p, v); }
; DI float quad_sum(float s) { s += __shfl_xor(s, 16); s += __shfl_xor(s, 32); return s; }
;     DI void operator()(const f32x4 (&acc)[2][2][4][2], const Unit& u, int wr, int wc, int fr, int fq) const {
;     ...
;                 const int row = row0 + ai * 128 + m * 16; float ss = 0.f;
;                 const float bs = (B16 && base) ? base[row] : 1.0f;
; #pragma unroll
;                 for (int bj = 0; bj < 2; ++bj) {
;                     const size_t off = (size_t)row * DM + col0 + bj * 128;
;                     f32x4 b0, b1;
;                     if (B16) { const u32x4 bb = *(const u32x4*)(base16 + off); b0 = (f32x4){bflo(bb.x), bfhi(bb.x), bflo(bb.y), bfhi(bb.y)}; b1 = (f32x4){bflo(bb.z), bfhi(bb.z), bflo(bb.w), bfhi(bb.w)}; b0 = b0 * bs; b1 = b1 * bs; }
;                     else { b0 = *(const f32x4*)(base + off); b1 = *(const f32x4*)(base + off + 4); }
;                     const f32x4 o0 = b0 + acc[ai][bj][m][0] * alpha, o1 = b1 + acc[ai][bj][m][1] * alpha;
;                     if (WOUT) { *(f32x4*)(out + off) = o0; *(f32x4*)(out + off + 4) = o1; }
;                     if (WB) { ss += (o0[0] * o0[0] + o0[1] * o0[1]) + (o0[2] * o0[2] + o0[3] * o0[3]) + (o1[0] * o1[0] + o1[1] * o1[1]) + (o1[2] * o1[2] + o1[3] * o1[3]);
;                         u32x4 w; w.x = pk2(o0[0], o0[1]); w.y = pk2(o0[2], o0[3]); w.z = pk2(o1[0], o1[1]); w.w = pk2(o1[2], o1[3]); *(u32x4*)(xb + off) = w; }
;                 }
;                 if (WB) { ss = quad_sum(ss); if (fq == 0) atomic_addf(P + row, ss); }
.LBB0_1745:
	s_or_b64 exec, exec, s[12:13]
	v_or_b32_e32 v80, 48, v146
	s_waitcnt lgkmcnt(0)
	v_ashrrev_i32_e32 v81, 31, v80
	v_lshlrev_b64 v[82:83], 10, v[80:81]
	v_lshl_add_u64 v[82:83], v[82:83], 0, v[144:145]
	v_lshlrev_b64 v[90:91], 1, v[82:83]
	v_lshl_add_u64 v[82:83], s[8:9], 0, v[90:91]
	v_lshl_add_u64 v[92:93], s[10:11], 0, v[90:91]
	v_or_b32_e32 v90, 0x100, v90
	s_nop 0
	v_lshl_add_u64 v[86:87], s[8:9], 0, v[90:91]
	s_nop 0
	v_lshlrev_b32_e32 v94, 16, v222
	v_and_b32_e32 v95, 0xffff0000, v222
	v_lshlrev_b32_e32 v82, 16, v223
	v_and_b32_e32 v83, 0xffff0000, v223
	v_lshlrev_b32_e32 v96, 16, v224
	v_and_b32_e32 v97, 0xffff0000, v224
	v_lshlrev_b32_e32 v84, 16, v225
	v_and_b32_e32 v85, 0xffff0000, v225
	v_pk_add_f32 v[76:77], v[76:77], v[94:95]
	v_lshlrev_b32_e32 v94, 16, v226
	v_and_b32_e32 v95, 0xffff0000, v226
	v_lshlrev_b32_e32 v86, 16, v227
	v_and_b32_e32 v87, 0xffff0000, v227
	v_pk_add_f32 v[78:79], v[78:79], v[82:83]
	v_pk_add_f32 v[82:83], v[74:75], v[84:85]
	v_pk_add_f32 v[84:85], v[72:73], v[96:97]
	v_lshlrev_b32_e32 v96, 16, v228
	v_and_b32_e32 v97, 0xffff0000, v228
	v_lshlrev_b32_e32 v88, 16, v229
	v_and_b32_e32 v89, 0xffff0000, v229
	v_add_u32_e32 v184, 0x40000, v190
	v_mov_b32_e32 v185, v191
	v_lshl_add_u64 v[186:187], s[8:9], 0, v[184:185]
	global_load_dwordx4 v[198:201], v[186:187], off
	global_load_dwordx4 v[202:205], v[186:187], off offset:256
	v_add_u32_e32 v184, 0x48000, v190
	v_mov_b32_e32 v185, v191
	v_lshl_add_u64 v[186:187], s[8:9], 0, v[184:185]
	global_load_dwordx4 v[206:209], v[186:187], off
	global_load_dwordx4 v[210:213], v[186:187], off offset:256
	v_add_u32_e32 v184, 0x50000, v190
	v_mov_b32_e32 v185, v191
	v_lshl_add_u64 v[186:187], s[8:9], 0, v[184:185]
	global_load_dwordx4 v[214:217], v[186:187], off
	global_load_dwordx4 v[218:221], v[186:187], off offset:256
	v_add_u32_e32 v184, 0x58000, v190
	v_mov_b32_e32 v185, v191
	v_lshl_add_u64 v[186:187], s[8:9], 0, v[184:185]
	global_load_dwordx4 v[222:225], v[186:187], off
	global_load_dwordx4 v[226:229], v[186:187], off offset:256
	v_pk_add_f32 v[70:71], v[70:71], v[86:87]
	v_pk_add_f32 v[68:69], v[68:69], v[94:95]
	v_mul_f32_e32 v75, v77, v77
	v_mul_f32_e32 v98, v79, v79
	v_pk_add_f32 v[86:87], v[66:67], v[88:89]
	v_pk_add_f32 v[88:89], v[64:65], v[96:97]
	v_mul_f32_e32 v64, v69, v69
	v_mul_f32_e32 v65, v71, v71
	v_mul_f32_e32 v99, v85, v85
	v_fmac_f32_e32 v75, v76, v76
	v_fmac_f32_e32 v98, v78, v78
	v_mul_f32_e32 v66, v89, v89
	v_fmac_f32_e32 v64, v68, v68
	v_fmac_f32_e32 v65, v70, v70
	v_mul_f32_e32 v100, v83, v83
	v_fmac_f32_e32 v99, v84, v84
	v_mul_f32_e32 v67, v87, v87
	v_add_f32_e32 v75, v75, v98
	v_fmac_f32_e32 v66, v88, v88
	v_add_f32_e32 v64, v64, v65
	v_fmac_f32_e32 v100, v82, v82
	v_add_f32_e32 v75, v99, v75
	v_add_f32_e32 v64, v66, v64
	v_fmac_f32_e32 v67, v86, v86
	v_add_f32_e32 v65, v100, v75
	v_add_f32_e32 v64, v67, v64
	v_add_f32_e32 v64, v65, v64
	ds_bpermute_b32 v65, v156, v64
	v_cvt_pk_bf16_f32 v72, v76, v77
	v_cvt_pk_bf16_f32 v73, v78, v79
	v_cvt_pk_bf16_f32 v74, v84, v85
	v_cvt_pk_bf16_f32 v75, v82, v83
	s_waitcnt lgkmcnt(0)
	v_add_f32_e32 v64, v64, v65
	ds_bpermute_b32 v65, v155, v64
	v_cvt_pk_bf16_f32 v66, v68, v69
	v_cvt_pk_bf16_f32 v67, v70, v71
	v_cvt_pk_bf16_f32 v68, v88, v89
	v_cvt_pk_bf16_f32 v69, v86, v87
	v_lshl_add_u64 v[70:71], s[10:11], 0, v[90:91]
	flat_store_dwordx4 v[92:93], v[72:75]
	flat_store_dwordx4 v[70:71], v[66:69]
	s_and_saveexec_b64 s[12:13], s[2:3]
	s_cbranch_execz .LBB0_1747
	v_lshl_add_u64 v[66:67], v[80:81], 2, s[14:15]
	s_waitcnt lgkmcnt(0)
	v_add_f32_e32 v64, v64, v65
	global_atomic_add_f32 v[66:67], v64, off
.LBB0_1747:
	s_or_b64 exec, exec, s[12:13]
	v_add_u32_e32 v64, 0x80, v146
	s_waitcnt lgkmcnt(0)
	v_ashrrev_i32_e32 v65, 31, v64
	v_lshlrev_b64 v[66:67], 10, v[64:65]
	v_lshl_add_u64 v[66:67], v[66:67], 0, v[144:145]
	v_lshlrev_b64 v[74:75], 1, v[66:67]
	v_lshl_add_u64 v[66:67], s[8:9], 0, v[74:75]
	v_lshl_add_u64 v[76:77], s[10:11], 0, v[74:75]
	v_or_b32_e32 v74, 0x100, v74
	s_nop 0
	v_lshl_add_u64 v[70:71], s[8:9], 0, v[74:75]
	s_nop 0
	s_waitcnt vmcnt(2)
	v_lshlrev_b32_e32 v78, 16, v198
	v_and_b32_e32 v79, 0xffff0000, v198
	v_lshlrev_b32_e32 v66, 16, v199
	v_and_b32_e32 v67, 0xffff0000, v199
	v_lshlrev_b32_e32 v80, 16, v200
	v_and_b32_e32 v81, 0xffff0000, v200
	v_lshlrev_b32_e32 v68, 16, v201
	v_and_b32_e32 v69, 0xffff0000, v201
	v_pk_add_f32 v[60:61], v[60:61], v[78:79]
	v_lshlrev_b32_e32 v78, 16, v202
	v_and_b32_e32 v79, 0xffff0000, v202
	v_lshlrev_b32_e32 v70, 16, v203
	v_and_b32_e32 v71, 0xffff0000, v203
	v_pk_add_f32 v[62:63], v[62:63], v[66:67]
	v_pk_add_f32 v[66:67], v[58:59], v[68:69]
	v_pk_add_f32 v[68:69], v[56:57], v[80:81]
	v_lshlrev_b32_e32 v80, 16, v204
	v_and_b32_e32 v81, 0xffff0000, v204
	v_lshlrev_b32_e32 v72, 16, v205
	v_and_b32_e32 v73, 0xffff0000, v205
	v_pk_add_f32 v[54:55], v[54:55], v[70:71]
	v_pk_add_f32 v[52:53], v[52:53], v[78:79]
	v_mul_f32_e32 v59, v61, v61
	v_mul_f32_e32 v82, v63, v63
	v_pk_add_f32 v[70:71], v[50:51], v[72:73]
	v_pk_add_f32 v[72:73], v[48:49], v[80:81]
	v_mul_f32_e32 v48, v53, v53
	v_mul_f32_e32 v49, v55, v55
	v_mul_f32_e32 v83, v69, v69
	v_fmac_f32_e32 v59, v60, v60
	v_fmac_f32_e32 v82, v62, v62
	v_mul_f32_e32 v50, v73, v73
	v_fmac_f32_e32 v48, v52, v52
	v_fmac_f32_e32 v49, v54, v54
	v_mul_f32_e32 v84, v67, v67
	v_fmac_f32_e32 v83, v68, v68
	v_mul_f32_e32 v51, v71, v71
	v_add_f32_e32 v59, v59, v82
	v_fmac_f32_e32 v50, v72, v72
	v_add_f32_e32 v48, v48, v49
	v_fmac_f32_e32 v84, v66, v66
	v_add_f32_e32 v59, v83, v59
	v_add_f32_e32 v48, v50, v48
	v_fmac_f32_e32 v51, v70, v70
	v_add_f32_e32 v49, v84, v59
	v_add_f32_e32 v48, v51, v48
	v_add_f32_e32 v48, v49, v48
	ds_bpermute_b32 v49, v156, v48
	v_cvt_pk_bf16_f32 v56, v60, v61
	v_cvt_pk_bf16_f32 v57, v62, v63
	v_cvt_pk_bf16_f32 v58, v68, v69
	v_cvt_pk_bf16_f32 v59, v66, v67
	s_waitcnt lgkmcnt(0)
	v_add_f32_e32 v48, v48, v49
	ds_bpermute_b32 v49, v155, v48
	v_cvt_pk_bf16_f32 v50, v52, v53
	v_cvt_pk_bf16_f32 v51, v54, v55
	v_cvt_pk_bf16_f32 v52, v72, v73
	v_cvt_pk_bf16_f32 v53, v70, v71
	v_lshl_add_u64 v[54:55], s[10:11], 0, v[74:75]
	flat_store_dwordx4 v[76:77], v[56:59]
	flat_store_dwordx4 v[54:55], v[50:53]
	s_and_saveexec_b64 s[12:13], s[2:3]
	s_cbranch_execz .LBB0_1749
	v_lshl_add_u64 v[50:51], v[64:65], 2, s[14:15]
	s_waitcnt lgkmcnt(0)
	v_add_f32_e32 v48, v48, v49
	global_atomic_add_f32 v[50:51], v48, off
; DI unsigned pk2(float lo, float hi) { typedef float v2f __attribute__((ext_vector_type(2))); typedef __bf16 v2b __attribute__((ext_vector_type(2))); v2f v = {lo, hi}; v2b b = __builtin_convertvector(v, v2b); return __builtin_bit_cast(unsigned, b); }
; DI float bflo(unsigned w) { return __uint_as_float(w << 16); }
; DI float bfhi(unsigned w) { return __uint_as_float(w & 0xffff0000u); }
; DI void atomic_addf(float* p, float v) { __builtin_amdgcn_global_atomic_fadd_f32((__attribute__((address_space(1))) float*)p, v); }
; DI float quad_sum(float s) { s += __shfl_xor(s, 16); s += __shfl_xor(s, 32); return s; }
;     DI void operator()(const f32x4 (&acc)[2][2][4][2], const Unit& u, int wr, int wc, int fr, int fq) const {
;     ...
;                 const int row = row0 + ai * 128 + m * 16; float ss = 0.f;
;                 const float bs = (B16 && base) ? base[row] : 1.0f;
; #pragma unroll
;                 for (int bj = 0; bj < 2; ++bj) {
;                     const size_t off = (size_t)row * DM + col0 + bj * 128;
;                     f32x4 b0, b1;
;                     if (B16) { const u32x4 bb = *(const u32x4*)(base16 + off); b0 = (f32x4){bflo(bb.x), bfhi(bb.x), bflo(bb.y), bfhi(bb.y)}; b1 = (f32x4){bflo(bb.z), bfhi(bb.z), bflo(bb.w), bfhi(bb.w)}; b0 = b0 * bs; b1 = b1 * bs; }
;                     else { b0 = *(const f32x4*)(base + off); b1 = *(const f32x4*)(base + off + 4); }
;                     const f32x4 o0 = b0 + acc[ai][bj][m][0] * alpha, o1 = b1 + acc[ai][bj][m][1] * alpha;
;                     if (WOUT) { *(f32x4*)(out + off) = o0; *(f32x4*)(out + off + 4) = o1; }
;                     if (WB) { ss += (o0[0] * o0[0] + o0[1] * o0[1]) + (o0[2] * o0[2] + o0[3] * o0[3]) + (o1[0] * o1[0] + o1[1] * o1[1]) + (o1[2] * o1[2] + o1[3] * o1[3]);
;                         u32x4 w; w.x = pk2(o0[0], o0[1]); w.y = pk2(o0[2], o0[3]); w.z = pk2(o1[0], o1[1]); w.w = pk2(o1[2], o1[3]); *(u32x4*)(xb + off) = w; }
;                 }
;                 if (WB) { ss = quad_sum(ss); if (fq == 0) atomic_addf(P + row, ss); }
.LBB0_1749:
	s_or_b64 exec, exec, s[12:13]
	v_add_u32_e32 v48, 0x90, v146
	s_waitcnt lgkmcnt(0)
	v_ashrrev_i32_e32 v49, 31, v48
	v_lshlrev_b64 v[50:51], 10, v[48:49]
	v_lshl_add_u64 v[50:51], v[50:51], 0, v[144:145]
	v_lshlrev_b64 v[58:59], 1, v[50:51]
	v_lshl_add_u64 v[50:51], s[8:9], 0, v[58:59]
	v_lshl_add_u64 v[60:61], s[10:11], 0, v[58:59]
	v_or_b32_e32 v58, 0x100, v58
	s_nop 0
	v_lshl_add_u64 v[54:55], s[8:9], 0, v[58:59]
	s_nop 0
	v_lshlrev_b32_e32 v62, 16, v206
	v_and_b32_e32 v63, 0xffff0000, v206
	v_lshlrev_b32_e32 v50, 16, v207
	v_and_b32_e32 v51, 0xffff0000, v207
	v_lshlrev_b32_e32 v64, 16, v208
	v_and_b32_e32 v65, 0xffff0000, v208
	v_lshlrev_b32_e32 v52, 16, v209
	v_and_b32_e32 v53, 0xffff0000, v209
	v_pk_add_f32 v[44:45], v[44:45], v[62:63]
	v_lshlrev_b32_e32 v62, 16, v210
	v_and_b32_e32 v63, 0xffff0000, v210
	v_lshlrev_b32_e32 v54, 16, v211
	v_and_b32_e32 v55, 0xffff0000, v211
	v_pk_add_f32 v[46:47], v[46:47], v[50:51]
	v_pk_add_f32 v[50:51], v[42:43], v[52:53]
	v_pk_add_f32 v[52:53], v[40:41], v[64:65]
	v_lshlrev_b32_e32 v64, 16, v212
	v_and_b32_e32 v65, 0xffff0000, v212
	v_lshlrev_b32_e32 v56, 16, v213
	v_and_b32_e32 v57, 0xffff0000, v213
	v_pk_add_f32 v[38:39], v[38:39], v[54:55]
	v_pk_add_f32 v[36:37], v[36:37], v[62:63]
	v_mul_f32_e32 v43, v45, v45
	v_mul_f32_e32 v66, v47, v47
	v_pk_add_f32 v[54:55], v[34:35], v[56:57]
	v_pk_add_f32 v[56:57], v[32:33], v[64:65]
	v_mul_f32_e32 v32, v37, v37
	v_mul_f32_e32 v33, v39, v39
	v_mul_f32_e32 v67, v53, v53
	v_fmac_f32_e32 v43, v44, v44
	v_fmac_f32_e32 v66, v46, v46
	v_mul_f32_e32 v34, v57, v57
	v_fmac_f32_e32 v32, v36, v36
	v_fmac_f32_e32 v33, v38, v38
	v_mul_f32_e32 v68, v51, v51
	v_fmac_f32_e32 v67, v52, v52
	v_mul_f32_e32 v35, v55, v55
	v_add_f32_e32 v43, v43, v66
	v_fmac_f32_e32 v34, v56, v56
	v_add_f32_e32 v32, v32, v33
	v_fmac_f32_e32 v68, v50, v50
	v_add_f32_e32 v43, v67, v43
	v_add_f32_e32 v32, v34, v32
	v_fmac_f32_e32 v35, v54, v54
	v_add_f32_e32 v33, v68, v43
	v_add_f32_e32 v32, v35, v32
	v_add_f32_e32 v32, v33, v32
	ds_bpermute_b32 v33, v156, v32
	v_cvt_pk_bf16_f32 v40, v44, v45
	v_cvt_pk_bf16_f32 v41, v46, v47
	v_cvt_pk_bf16_f32 v42, v52, v53
	v_cvt_pk_bf16_f32 v43, v50, v51
	s_waitcnt lgkmcnt(0)
	v_add_f32_e32 v32, v32, v33
	ds_bpermute_b32 v33, v155, v32
	v_cvt_pk_bf16_f32 v34, v36, v37
	v_cvt_pk_bf16_f32 v35, v38, v39
	v_cvt_pk_bf16_f32 v36, v56, v57
	v_cvt_pk_bf16_f32 v37, v54, v55
	v_lshl_add_u64 v[38:39], s[10:11], 0, v[58:59]
	flat_store_dwordx4 v[60:61], v[40:43]
	flat_store_dwordx4 v[38:39], v[34:37]
	s_and_saveexec_b64 s[12:13], s[2:3]
	s_cbranch_execz .LBB0_1751
	v_lshl_add_u64 v[34:35], v[48:49], 2, s[14:15]
	s_waitcnt lgkmcnt(0)
	v_add_f32_e32 v32, v32, v33
	global_atomic_add_f32 v[34:35], v32, off
; DI unsigned pk2(float lo, float hi) { typedef float v2f __attribute__((ext_vector_type(2))); typedef __bf16 v2b __attribute__((ext_vector_type(2))); v2f v = {lo, hi}; v2b b = __builtin_convertvector(v, v2b); return __builtin_bit_cast(unsigned, b); }
; DI float bflo(unsigned w) { return __uint_as_float(w << 16); }
; DI float bfhi(unsigned w) { return __uint_as_float(w & 0xffff0000u); }
; DI void atomic_addf(float* p, float v) { __builtin_amdgcn_global_atomic_fadd_f32((__attribute__((address_space(1))) float*)p, v); }
; DI float quad_sum(float s) { s += __shfl_xor(s, 16); s += __shfl_xor(s, 32); return s; }
;     DI void operator()(const f32x4 (&acc)[2][2][4][2], const Unit& u, int wr, int wc, int fr, int fq) const {
;     ...
;                 const int row = row0 + ai * 128 + m * 16; float ss = 0.f;
;                 const float bs = (B16 && base) ? base[row] : 1.0f;
; #pragma unroll
;                 for (int bj = 0; bj < 2; ++bj) {
;                     const size_t off = (size_t)row * DM + col0 + bj * 128;
;                     f32x4 b0, b1;
;                     if (B16) { const u32x4 bb = *(const u32x4*)(base16 + off); b0 = (f32x4){bflo(bb.x), bfhi(bb.x), bflo(bb.y), bfhi(bb.y)}; b1 = (f32x4){bflo(bb.z), bfhi(bb.z), bflo(bb.w), bfhi(bb.w)}; b0 = b0 * bs; b1 = b1 * bs; }
;                     else { b0 = *(const f32x4*)(base + off); b1 = *(const f32x4*)(base + off + 4); }
;                     const f32x4 o0 = b0 + acc[ai][bj][m][0] * alpha, o1 = b1 + acc[ai][bj][m][1] * alpha;
;                     if (WOUT) { *(f32x4*)(out + off) = o0; *(f32x4*)(out + off + 4) = o1; }
;                     if (WB) { ss += (o0[0] * o0[0] + o0[1] * o0[1]) + (o0[2] * o0[2] + o0[3] * o0[3]) + (o1[0] * o1[0] + o1[1] * o1[1]) + (o1[2] * o1[2] + o1[3] * o1[3]);
;                         u32x4 w; w.x = pk2(o0[0], o0[1]); w.y = pk2(o0[2], o0[3]); w.z = pk2(o1[0], o1[1]); w.w = pk2(o1[2], o1[3]); *(u32x4*)(xb + off) = w; }
;                 }
;                 if (WB) { ss = quad_sum(ss); if (fq == 0) atomic_addf(P + row, ss); }
.LBB0_1751:
	s_or_b64 exec, exec, s[12:13]
	v_add_u32_e32 v32, 0xa0, v146
	s_waitcnt lgkmcnt(0)
	v_ashrrev_i32_e32 v33, 31, v32
	v_lshlrev_b64 v[34:35], 10, v[32:33]
	v_lshl_add_u64 v[34:35], v[34:35], 0, v[144:145]
	v_lshlrev_b64 v[42:43], 1, v[34:35]
	v_lshl_add_u64 v[34:35], s[8:9], 0, v[42:43]
	v_lshl_add_u64 v[44:45], s[10:11], 0, v[42:43]
	v_or_b32_e32 v42, 0x100, v42
	s_nop 0
	v_lshl_add_u64 v[38:39], s[8:9], 0, v[42:43]
	s_nop 0
	v_lshlrev_b32_e32 v46, 16, v214
	v_and_b32_e32 v47, 0xffff0000, v214
	v_lshlrev_b32_e32 v34, 16, v215
	v_and_b32_e32 v35, 0xffff0000, v215
	v_lshlrev_b32_e32 v48, 16, v216
	v_and_b32_e32 v49, 0xffff0000, v216
	v_lshlrev_b32_e32 v36, 16, v217
	v_and_b32_e32 v37, 0xffff0000, v217
	v_pk_add_f32 v[28:29], v[28:29], v[46:47]
	v_lshlrev_b32_e32 v46, 16, v218
	v_and_b32_e32 v47, 0xffff0000, v218
	v_lshlrev_b32_e32 v38, 16, v219
	v_and_b32_e32 v39, 0xffff0000, v219
	v_pk_add_f32 v[30:31], v[30:31], v[34:35]
	v_pk_add_f32 v[34:35], v[26:27], v[36:37]
	v_pk_add_f32 v[36:37], v[24:25], v[48:49]
	v_lshlrev_b32_e32 v48, 16, v220
	v_and_b32_e32 v49, 0xffff0000, v220
	v_lshlrev_b32_e32 v40, 16, v221
	v_and_b32_e32 v41, 0xffff0000, v221
	v_pk_add_f32 v[22:23], v[22:23], v[38:39]
	v_pk_add_f32 v[20:21], v[20:21], v[46:47]
	v_mul_f32_e32 v27, v29, v29
	v_mul_f32_e32 v50, v31, v31
	v_pk_add_f32 v[38:39], v[18:19], v[40:41]
	v_pk_add_f32 v[40:41], v[16:17], v[48:49]
	v_mul_f32_e32 v16, v21, v21
	v_mul_f32_e32 v17, v23, v23
	v_mul_f32_e32 v51, v37, v37
	v_fmac_f32_e32 v27, v28, v28
	v_fmac_f32_e32 v50, v30, v30
	v_mul_f32_e32 v18, v41, v41
	v_fmac_f32_e32 v16, v20, v20
	v_fmac_f32_e32 v17, v22, v22
	v_mul_f32_e32 v52, v35, v35
	v_fmac_f32_e32 v51, v36, v36
	v_mul_f32_e32 v19, v39, v39
	v_add_f32_e32 v27, v27, v50
	v_fmac_f32_e32 v18, v40, v40
	v_add_f32_e32 v16, v16, v17
	v_fmac_f32_e32 v52, v34, v34
	v_add_f32_e32 v27, v51, v27
	v_add_f32_e32 v16, v18, v16
	v_fmac_f32_e32 v19, v38, v38
	v_add_f32_e32 v17, v52, v27
	v_add_f32_e32 v16, v19, v16
	v_add_f32_e32 v16, v17, v16
	ds_bpermute_b32 v17, v156, v16
	v_cvt_pk_bf16_f32 v24, v28, v29
	v_cvt_pk_bf16_f32 v25, v30, v31
	v_cvt_pk_bf16_f32 v26, v36, v37
	v_cvt_pk_bf16_f32 v27, v34, v35
	s_waitcnt lgkmcnt(0)
	v_add_f32_e32 v16, v16, v17
	ds_bpermute_b32 v17, v155, v16
	v_cvt_pk_bf16_f32 v18, v20, v21
	v_cvt_pk_bf16_f32 v19, v22, v23
	v_cvt_pk_bf16_f32 v20, v40, v41
	v_cvt_pk_bf16_f32 v21, v38, v39
	v_lshl_add_u64 v[22:23], s[10:11], 0, v[42:43]
	flat_store_dwordx4 v[44:45], v[24:27]
	flat_store_dwordx4 v[22:23], v[18:21]
	s_and_saveexec_b64 s[12:13], s[2:3]
	s_cbranch_execz .LBB0_1753
	v_lshl_add_u64 v[18:19], v[32:33], 2, s[14:15]
	s_waitcnt lgkmcnt(0)
	v_add_f32_e32 v16, v16, v17
	global_atomic_add_f32 v[18:19], v16, off
.LBB0_1753:
	s_or_b64 exec, exec, s[12:13]
	v_add_u32_e32 v16, 0xb0, v146
	s_waitcnt lgkmcnt(0)
	v_ashrrev_i32_e32 v17, 31, v16
	v_lshlrev_b64 v[18:19], 10, v[16:17]
	v_lshl_add_u64 v[18:19], v[18:19], 0, v[144:145]
	v_lshlrev_b64 v[26:27], 1, v[18:19]
	v_lshl_add_u64 v[18:19], s[8:9], 0, v[26:27]
	v_lshl_add_u64 v[28:29], s[10:11], 0, v[26:27]
	v_or_b32_e32 v26, 0x100, v26
	s_nop 0
	v_lshl_add_u64 v[22:23], s[8:9], 0, v[26:27]
	s_nop 0
	v_lshlrev_b32_e32 v30, 16, v222
	v_and_b32_e32 v31, 0xffff0000, v222
	v_lshlrev_b32_e32 v18, 16, v223
	v_and_b32_e32 v19, 0xffff0000, v223
	v_lshlrev_b32_e32 v32, 16, v224
	v_and_b32_e32 v33, 0xffff0000, v224
	v_lshlrev_b32_e32 v20, 16, v225
	v_and_b32_e32 v21, 0xffff0000, v225
	v_pk_add_f32 v[12:13], v[12:13], v[30:31]
	v_lshlrev_b32_e32 v30, 16, v226
	v_and_b32_e32 v31, 0xffff0000, v226
	v_lshlrev_b32_e32 v22, 16, v227
	v_and_b32_e32 v23, 0xffff0000, v227
	v_pk_add_f32 v[14:15], v[14:15], v[18:19]
	v_pk_add_f32 v[18:19], v[10:11], v[20:21]
	v_pk_add_f32 v[20:21], v[8:9], v[32:33]
	v_lshlrev_b32_e32 v32, 16, v228
	v_and_b32_e32 v33, 0xffff0000, v228
	v_lshlrev_b32_e32 v24, 16, v229
	v_and_b32_e32 v25, 0xffff0000, v229
	v_pk_add_f32 v[6:7], v[6:7], v[22:23]
	v_pk_add_f32 v[4:5], v[4:5], v[30:31]
	v_mul_f32_e32 v11, v13, v13
	v_mul_f32_e32 v34, v15, v15
	v_pk_add_f32 v[22:23], v[2:3], v[24:25]
	v_pk_add_f32 v[24:25], v[0:1], v[32:33]
	v_mul_f32_e32 v0, v5, v5
	v_mul_f32_e32 v1, v7, v7
	v_mul_f32_e32 v35, v21, v21
	v_fmac_f32_e32 v11, v12, v12
	v_fmac_f32_e32 v34, v14, v14
	v_mul_f32_e32 v2, v25, v25
	v_fmac_f32_e32 v0, v4, v4
	v_fmac_f32_e32 v1, v6, v6
	v_mul_f32_e32 v36, v19, v19
	v_fmac_f32_e32 v35, v20, v20
	v_mul_f32_e32 v3, v23, v23
	v_add_f32_e32 v11, v11, v34
	v_fmac_f32_e32 v2, v24, v24
	v_add_f32_e32 v0, v0, v1
	v_fmac_f32_e32 v36, v18, v18
	v_add_f32_e32 v11, v35, v11
	v_add_f32_e32 v0, v2, v0
	v_fmac_f32_e32 v3, v22, v22
	v_add_f32_e32 v1, v36, v11
	v_add_f32_e32 v0, v3, v0
	v_add_f32_e32 v0, v1, v0
	ds_bpermute_b32 v1, v156, v0
	v_cvt_pk_bf16_f32 v8, v12, v13
	v_cvt_pk_bf16_f32 v9, v14, v15
	v_cvt_pk_bf16_f32 v10, v20, v21
	v_cvt_pk_bf16_f32 v11, v18, v19
	s_waitcnt lgkmcnt(0)
	v_add_f32_e32 v0, v0, v1
	ds_bpermute_b32 v1, v155, v0
	v_cvt_pk_bf16_f32 v2, v4, v5
	v_cvt_pk_bf16_f32 v3, v6, v7
	v_cvt_pk_bf16_f32 v4, v24, v25
	v_cvt_pk_bf16_f32 v5, v22, v23
	v_lshl_add_u64 v[6:7], s[10:11], 0, v[26:27]
	flat_store_dwordx4 v[28:29], v[8:11]
	flat_store_dwordx4 v[6:7], v[2:5]
	s_and_saveexec_b64 s[12:13], s[2:3]
	s_cbranch_execz .LBB0_1755
	v_lshl_add_u64 v[2:3], v[16:17], 2, s[14:15]
	s_waitcnt lgkmcnt(0)
	v_add_f32_e32 v0, v0, v1
	global_atomic_add_f32 v[2:3], v0, off

; DI float bflo(unsigned w) { return __uint_as_float(w << 16); }
; DI float bfhi(unsigned w) { return __uint_as_float(w & 0xffff0000u); }
;     DI void operator()(const f32x4 (&acc)[2][2][4][2], const Unit& u, int wr, int wc, int fr, int fq) const {
;     ...
;                 const int row = row0 + ai * 128 + m * 16; float ss = 0.f;
;                 const float bs = (B16 && base) ? base[row] : 1.0f;
; #pragma unroll
;                 for (int bj = 0; bj < 2; ++bj) {
;                     const size_t off = (size_t)row * DM + col0 + bj * 128;
;                     f32x4 b0, b1;
;                     if (B16) { const u32x4 bb = *(const u32x4*)(base16 + off); b0 = (f32x4){bflo(bb.x), bfhi(bb.x), bflo(bb.y), bfhi(bb.y)}; b1 = (f32x4){bflo(bb.z), bfhi(bb.z), bflo(bb.w), bfhi(bb.w)}; b0 = b0 * bs; b1 = b1 * bs; }
;                     else { b0 = *(const f32x4*)(base + off); b1 = *(const f32x4*)(base + off + 4); }
;                     const f32x4 o0 = b0 + acc[ai][bj][m][0] * alpha, o1 = b1 + acc[ai][bj][m][1] * alpha;
;                     if (WOUT) { *(f32x4*)(out + off) = o0; *(f32x4*)(out + off + 4) = o1; }
.LBB0_1905:
	v_lshl_add_u32 v148, s49, 8, v150
	v_lshl_or_b32 v146, s50, 8, v152
	v_ashrrev_i32_e32 v149, 31, v148
	v_ashrrev_i32_e32 v147, 31, v146
	v_lshlrev_b64 v[144:145], 10, v[148:149]
	v_lshl_add_u64 v[144:145], v[144:145], 0, v[146:147]
	v_lshlrev_b64 v[160:161], 1, v[144:145]
	v_mov_b32_e32 v172, v160
	v_mov_b32_e32 v173, v161
	v_mov_b32_e32 v168, v172
	v_mov_b32_e32 v169, v173
	v_lshl_add_u64 v[170:171], s[6:7], 0, v[168:169]
	global_load_dwordx4 v[224:227], v[170:171], off
	global_load_dwordx4 v[228:231], v[170:171], off offset:256
	v_add_u32_e32 v168, 0x8000, v172
	v_mov_b32_e32 v169, v173
	v_lshl_add_u64 v[170:171], s[6:7], 0, v[168:169]
	global_load_dwordx4 v[232:235], v[170:171], off
	global_load_dwordx4 v[236:239], v[170:171], off offset:256
	v_add_u32_e32 v168, 0x10000, v172
	v_mov_b32_e32 v169, v173
	v_lshl_add_u64 v[170:171], s[6:7], 0, v[168:169]
	global_load_dwordx4 v[240:243], v[170:171], off
	global_load_dwordx4 v[244:247], v[170:171], off offset:256
	v_add_u32_e32 v168, 0x18000, v172
	v_mov_b32_e32 v169, v173
	v_lshl_add_u64 v[170:171], s[6:7], 0, v[168:169]
	global_load_dwordx4 v[248:251], v[170:171], off
	global_load_dwordx4 v[252:255], v[170:171], off offset:256
	v_lshl_add_u64 v[156:157], s[6:7], 0, v[160:161]
	s_nop 0
	v_lshl_add_u64 v[162:163], v[144:145], 2, s[28:29]
	v_or_b32_e32 v160, 0x100, v160
	v_lshl_add_u64 v[160:161], s[6:7], 0, v[160:161]
	s_and_b64 vcc, exec, s[0:1]
	s_mov_b64 s[0:1], -1
	s_waitcnt vmcnt(0)
	v_lshlrev_b32_e32 v164, 16, v224
	v_and_b32_e32 v165, 0xffff0000, v224
	v_lshlrev_b32_e32 v156, 16, v225
	v_and_b32_e32 v157, 0xffff0000, v225
	v_lshlrev_b32_e32 v166, 16, v226
	v_and_b32_e32 v167, 0xffff0000, v226
	v_lshlrev_b32_e32 v158, 16, v227
	v_and_b32_e32 v159, 0xffff0000, v227
	v_pk_fma_f32 v[126:127], v[126:127], 0.5, v[156:157] op_sel_hi:[1,0,1]
	v_pk_fma_f32 v[124:125], v[124:125], 0.5, v[164:165] op_sel_hi:[1,0,1]
	v_pk_fma_f32 v[122:123], v[122:123], 0.5, v[158:159] op_sel_hi:[1,0,1]
	v_pk_fma_f32 v[120:121], v[120:121], 0.5, v[166:167] op_sel_hi:[1,0,1]
	global_store_dwordx4 v[162:163], v[124:127], off
	global_store_dwordx4 v[162:163], v[120:123], off offset:16
	s_nop 0
	v_or_b32_e32 v124, 16, v148
	v_ashrrev_i32_e32 v125, 31, v124
	v_lshlrev_b64 v[124:125], 10, v[124:125]
	v_lshl_add_u64 v[124:125], v[124:125], 0, v[146:147]
	v_lshlrev_b64 v[126:127], 1, v[124:125]
	v_lshl_add_u64 v[156:157], s[6:7], 0, v[126:127]
	v_or_b32_e32 v126, 0x100, v126
	v_lshlrev_b32_e32 v158, 16, v228
	v_and_b32_e32 v159, 0xffff0000, v228
	v_lshlrev_b32_e32 v120, 16, v229
	v_and_b32_e32 v121, 0xffff0000, v229
	v_lshlrev_b32_e32 v160, 16, v230
	v_and_b32_e32 v161, 0xffff0000, v230
	v_lshlrev_b32_e32 v122, 16, v231
	v_and_b32_e32 v123, 0xffff0000, v231
	v_pk_fma_f32 v[118:119], v[118:119], 0.5, v[120:121] op_sel_hi:[1,0,1]
	v_pk_fma_f32 v[116:117], v[116:117], 0.5, v[158:159] op_sel_hi:[1,0,1]
	v_pk_fma_f32 v[114:115], v[114:115], 0.5, v[122:123] op_sel_hi:[1,0,1]
	v_pk_fma_f32 v[112:113], v[112:113], 0.5, v[160:161] op_sel_hi:[1,0,1]
	global_store_dwordx4 v[162:163], v[116:119], off offset:512
	global_store_dwordx4 v[162:163], v[112:115], off offset:528
	s_nop 0
	v_lshl_add_u64 v[116:117], v[124:125], 2, s[28:29]
	v_lshl_add_u64 v[118:119], s[6:7], 0, v[126:127]
	v_lshlrev_b32_e32 v120, 16, v232
	v_and_b32_e32 v121, 0xffff0000, v232
	v_lshlrev_b32_e32 v112, 16, v233
	v_and_b32_e32 v113, 0xffff0000, v233
	v_lshlrev_b32_e32 v122, 16, v234
	v_and_b32_e32 v123, 0xffff0000, v234
	v_lshlrev_b32_e32 v114, 16, v235
	v_and_b32_e32 v115, 0xffff0000, v235
	v_pk_fma_f32 v[110:111], v[110:111], 0.5, v[112:113] op_sel_hi:[1,0,1]
	v_pk_fma_f32 v[108:109], v[108:109], 0.5, v[120:121] op_sel_hi:[1,0,1]
	v_pk_fma_f32 v[106:107], v[106:107], 0.5, v[114:115] op_sel_hi:[1,0,1]
	v_pk_fma_f32 v[104:105], v[104:105], 0.5, v[122:123] op_sel_hi:[1,0,1]
	global_store_dwordx4 v[116:117], v[108:111], off
	global_store_dwordx4 v[116:117], v[104:107], off offset:16
	s_nop 0
	v_or_b32_e32 v108, 32, v148
	v_ashrrev_i32_e32 v109, 31, v108
	v_lshlrev_b64 v[108:109], 10, v[108:109]
	v_lshl_add_u64 v[108:109], v[108:109], 0, v[146:147]
	v_lshlrev_b64 v[110:111], 1, v[108:109]
	v_lshl_add_u64 v[112:113], s[6:7], 0, v[110:111]
	v_or_b32_e32 v110, 0x100, v110
	v_lshlrev_b32_e32 v114, 16, v236
	v_and_b32_e32 v115, 0xffff0000, v236
	v_lshlrev_b32_e32 v104, 16, v237
	v_and_b32_e32 v105, 0xffff0000, v237
	v_lshlrev_b32_e32 v118, 16, v238
	v_and_b32_e32 v119, 0xffff0000, v238
	v_lshlrev_b32_e32 v106, 16, v239
	v_and_b32_e32 v107, 0xffff0000, v239
	v_pk_fma_f32 v[102:103], v[102:103], 0.5, v[104:105] op_sel_hi:[1,0,1]
	v_pk_fma_f32 v[100:101], v[100:101], 0.5, v[114:115] op_sel_hi:[1,0,1]
	v_pk_fma_f32 v[98:99], v[98:99], 0.5, v[106:107] op_sel_hi:[1,0,1]
	v_pk_fma_f32 v[96:97], v[96:97], 0.5, v[118:119] op_sel_hi:[1,0,1]
	global_store_dwordx4 v[116:117], v[100:103], off offset:512
	global_store_dwordx4 v[116:117], v[96:99], off offset:528
	s_nop 0
	v_lshl_add_u64 v[100:101], v[108:109], 2, s[28:29]
	v_lshl_add_u64 v[102:103], s[6:7], 0, v[110:111]
	v_lshlrev_b32_e32 v104, 16, v240
	v_and_b32_e32 v105, 0xffff0000, v240
	v_lshlrev_b32_e32 v96, 16, v241
	v_and_b32_e32 v97, 0xffff0000, v241
	v_lshlrev_b32_e32 v106, 16, v242
	v_and_b32_e32 v107, 0xffff0000, v242
	v_lshlrev_b32_e32 v98, 16, v243
	v_and_b32_e32 v99, 0xffff0000, v243
	v_pk_fma_f32 v[94:95], v[94:95], 0.5, v[96:97] op_sel_hi:[1,0,1]
	v_pk_fma_f32 v[92:93], v[92:93], 0.5, v[104:105] op_sel_hi:[1,0,1]
	v_pk_fma_f32 v[90:91], v[90:91], 0.5, v[98:99] op_sel_hi:[1,0,1]
	v_pk_fma_f32 v[88:89], v[88:89], 0.5, v[106:107] op_sel_hi:[1,0,1]
	global_store_dwordx4 v[100:101], v[92:95], off
; DI float bflo(unsigned w) { return __uint_as_float(w << 16); }
; DI float bfhi(unsigned w) { return __uint_as_float(w & 0xffff0000u); }
;     DI void operator()(const f32x4 (&acc)[2][2][4][2], const Unit& u, int wr, int wc, int fr, int fq) const {
;     ...
;                 const int row = row0 + ai * 128 + m * 16; float ss = 0.f;
;                 const float bs = (B16 && base) ? base[row] : 1.0f;
; #pragma unroll
;                 for (int bj = 0; bj < 2; ++bj) {
;                     const size_t off = (size_t)row * DM + col0 + bj * 128;
;                     f32x4 b0, b1;
;                     if (B16) { const u32x4 bb = *(const u32x4*)(base16 + off); b0 = (f32x4){bflo(bb.x), bfhi(bb.x), bflo(bb.y), bfhi(bb.y)}; b1 = (f32x4){bflo(bb.z), bfhi(bb.z), bflo(bb.w), bfhi(bb.w)}; b0 = b0 * bs; b1 = b1 * bs; }
;                     else { b0 = *(const f32x4*)(base + off); b1 = *(const f32x4*)(base + off + 4); }
;                     const f32x4 o0 = b0 + acc[ai][bj][m][0] * alpha, o1 = b1 + acc[ai][bj][m][1] * alpha;
;                     if (WOUT) { *(f32x4*)(out + off) = o0; *(f32x4*)(out + off + 4) = o1; }
	global_store_dwordx4 v[100:101], v[88:91], off offset:16
	s_nop 0
	v_or_b32_e32 v92, 48, v148
	v_ashrrev_i32_e32 v93, 31, v92
	v_lshlrev_b64 v[92:93], 10, v[92:93]
	v_lshl_add_u64 v[92:93], v[92:93], 0, v[146:147]
	v_lshlrev_b64 v[94:95], 1, v[92:93]
	v_lshl_add_u64 v[96:97], s[6:7], 0, v[94:95]
	v_or_b32_e32 v94, 0x100, v94
	v_lshlrev_b32_e32 v98, 16, v244
	v_and_b32_e32 v99, 0xffff0000, v244
	v_lshlrev_b32_e32 v88, 16, v245
	v_and_b32_e32 v89, 0xffff0000, v245
	v_lshlrev_b32_e32 v102, 16, v246
	v_and_b32_e32 v103, 0xffff0000, v246
	v_lshlrev_b32_e32 v90, 16, v247
	v_and_b32_e32 v91, 0xffff0000, v247
	v_pk_fma_f32 v[86:87], v[86:87], 0.5, v[88:89] op_sel_hi:[1,0,1]
	v_pk_fma_f32 v[84:85], v[84:85], 0.5, v[98:99] op_sel_hi:[1,0,1]
	v_pk_fma_f32 v[82:83], v[82:83], 0.5, v[90:91] op_sel_hi:[1,0,1]
	v_pk_fma_f32 v[80:81], v[80:81], 0.5, v[102:103] op_sel_hi:[1,0,1]
	global_store_dwordx4 v[100:101], v[84:87], off offset:512
	global_store_dwordx4 v[100:101], v[80:83], off offset:528
	s_nop 0
	v_lshl_add_u64 v[84:85], v[92:93], 2, s[28:29]
	v_lshl_add_u64 v[86:87], s[6:7], 0, v[94:95]
	v_lshlrev_b32_e32 v88, 16, v248
	v_and_b32_e32 v89, 0xffff0000, v248
	v_lshlrev_b32_e32 v80, 16, v249
	v_and_b32_e32 v81, 0xffff0000, v249
	v_lshlrev_b32_e32 v90, 16, v250
	v_and_b32_e32 v91, 0xffff0000, v250
	v_lshlrev_b32_e32 v82, 16, v251
	v_and_b32_e32 v83, 0xffff0000, v251
	v_pk_fma_f32 v[78:79], v[78:79], 0.5, v[80:81] op_sel_hi:[1,0,1]
	v_pk_fma_f32 v[76:77], v[76:77], 0.5, v[88:89] op_sel_hi:[1,0,1]
	v_pk_fma_f32 v[74:75], v[74:75], 0.5, v[82:83] op_sel_hi:[1,0,1]
	v_pk_fma_f32 v[72:73], v[72:73], 0.5, v[90:91] op_sel_hi:[1,0,1]
	global_store_dwordx4 v[84:85], v[76:79], off
	global_store_dwordx4 v[84:85], v[72:75], off offset:16
	s_nop 0
	v_lshl_add_u64 v[76:77], v[144:145], 0, s[14:15]
	v_lshlrev_b64 v[78:79], 1, v[76:77]
	v_lshl_add_u64 v[80:81], s[6:7], 0, v[78:79]
	v_or_b32_e32 v78, 0x100, v78
	v_lshlrev_b32_e32 v82, 16, v252
	v_and_b32_e32 v83, 0xffff0000, v252
	v_lshlrev_b32_e32 v72, 16, v253
	v_and_b32_e32 v73, 0xffff0000, v253
	v_lshlrev_b32_e32 v86, 16, v254
	v_and_b32_e32 v87, 0xffff0000, v254
	v_lshlrev_b32_e32 v74, 16, v255
	v_and_b32_e32 v75, 0xffff0000, v255
	v_add_u32_e32 v168, 0x40000, v172
	v_mov_b32_e32 v169, v173
	v_lshl_add_u64 v[170:171], s[6:7], 0, v[168:169]
	global_load_dwordx4 v[224:227], v[170:171], off
	global_load_dwordx4 v[228:231], v[170:171], off offset:256
	v_add_u32_e32 v168, 0x48000, v172
	v_mov_b32_e32 v169, v173
	v_lshl_add_u64 v[170:171], s[6:7], 0, v[168:169]
	global_load_dwordx4 v[232:235], v[170:171], off
	global_load_dwordx4 v[236:239], v[170:171], off offset:256
	v_add_u32_e32 v168, 0x50000, v172
	v_mov_b32_e32 v169, v173
	v_lshl_add_u64 v[170:171], s[6:7], 0, v[168:169]
	global_load_dwordx4 v[240:243], v[170:171], off
	global_load_dwordx4 v[244:247], v[170:171], off offset:256
	v_add_u32_e32 v168, 0x58000, v172
	v_mov_b32_e32 v169, v173
	v_lshl_add_u64 v[170:171], s[6:7], 0, v[168:169]
	global_load_dwordx4 v[248:251], v[170:171], off
	global_load_dwordx4 v[252:255], v[170:171], off offset:256
	v_pk_fma_f32 v[70:71], v[70:71], 0.5, v[72:73] op_sel_hi:[1,0,1]
	v_pk_fma_f32 v[68:69], v[68:69], 0.5, v[82:83] op_sel_hi:[1,0,1]
	v_pk_fma_f32 v[66:67], v[66:67], 0.5, v[74:75] op_sel_hi:[1,0,1]
	v_pk_fma_f32 v[64:65], v[64:65], 0.5, v[86:87] op_sel_hi:[1,0,1]
	global_store_dwordx4 v[84:85], v[68:71], off offset:512
	global_store_dwordx4 v[84:85], v[64:67], off offset:528
	s_nop 0
	v_lshl_add_u64 v[68:69], v[76:77], 2, s[28:29]
	v_lshl_add_u64 v[70:71], s[6:7], 0, v[78:79]
	s_waitcnt vmcnt(2)
; DI float bflo(unsigned w) { return __uint_as_float(w << 16); }
; DI float bfhi(unsigned w) { return __uint_as_float(w & 0xffff0000u); }
;     DI void operator()(const f32x4 (&acc)[2][2][4][2], const Unit& u, int wr, int wc, int fr, int fq) const {
;     ...
;                 const int row = row0 + ai * 128 + m * 16; float ss = 0.f;
;                 const float bs = (B16 && base) ? base[row] : 1.0f;
; #pragma unroll
;                 for (int bj = 0; bj < 2; ++bj) {
;                     const size_t off = (size_t)row * DM + col0 + bj * 128;
;                     f32x4 b0, b1;
;                     if (B16) { const u32x4 bb = *(const u32x4*)(base16 + off); b0 = (f32x4){bflo(bb.x), bfhi(bb.x), bflo(bb.y), bfhi(bb.y)}; b1 = (f32x4){bflo(bb.z), bfhi(bb.z), bflo(bb.w), bfhi(bb.w)}; b0 = b0 * bs; b1 = b1 * bs; }
;                     else { b0 = *(const f32x4*)(base + off); b1 = *(const f32x4*)(base + off + 4); }
;                     const f32x4 o0 = b0 + acc[ai][bj][m][0] * alpha, o1 = b1 + acc[ai][bj][m][1] * alpha;
;                     if (WOUT) { *(f32x4*)(out + off) = o0; *(f32x4*)(out + off + 4) = o1; }
	v_lshlrev_b32_e32 v72, 16, v224
	v_and_b32_e32 v73, 0xffff0000, v224
	v_lshlrev_b32_e32 v64, 16, v225
	v_and_b32_e32 v65, 0xffff0000, v225
	v_lshlrev_b32_e32 v74, 16, v226
	v_and_b32_e32 v75, 0xffff0000, v226
	v_lshlrev_b32_e32 v66, 16, v227
	v_and_b32_e32 v67, 0xffff0000, v227
	v_pk_fma_f32 v[62:63], v[62:63], 0.5, v[64:65] op_sel_hi:[1,0,1]
	v_pk_fma_f32 v[60:61], v[60:61], 0.5, v[72:73] op_sel_hi:[1,0,1]
	v_pk_fma_f32 v[58:59], v[58:59], 0.5, v[66:67] op_sel_hi:[1,0,1]
	v_pk_fma_f32 v[56:57], v[56:57], 0.5, v[74:75] op_sel_hi:[1,0,1]
	global_store_dwordx4 v[68:69], v[60:63], off
	global_store_dwordx4 v[68:69], v[56:59], off offset:16
	s_nop 0
	v_lshl_add_u64 v[60:61], v[144:145], 0, s[16:17]
	v_lshlrev_b64 v[62:63], 1, v[60:61]
	v_lshl_add_u64 v[64:65], s[6:7], 0, v[62:63]
	v_or_b32_e32 v62, 0x100, v62
	v_lshlrev_b32_e32 v66, 16, v228
	v_and_b32_e32 v67, 0xffff0000, v228
	v_lshlrev_b32_e32 v56, 16, v229
	v_and_b32_e32 v57, 0xffff0000, v229
	v_lshlrev_b32_e32 v70, 16, v230
	v_and_b32_e32 v71, 0xffff0000, v230
	v_lshlrev_b32_e32 v58, 16, v231
	v_and_b32_e32 v59, 0xffff0000, v231
	v_pk_fma_f32 v[54:55], v[54:55], 0.5, v[56:57] op_sel_hi:[1,0,1]
	v_pk_fma_f32 v[52:53], v[52:53], 0.5, v[66:67] op_sel_hi:[1,0,1]
	v_pk_fma_f32 v[50:51], v[50:51], 0.5, v[58:59] op_sel_hi:[1,0,1]
	v_pk_fma_f32 v[48:49], v[48:49], 0.5, v[70:71] op_sel_hi:[1,0,1]
	global_store_dwordx4 v[68:69], v[52:55], off offset:512
	global_store_dwordx4 v[68:69], v[48:51], off offset:528
	s_nop 0
	v_lshl_add_u64 v[52:53], v[60:61], 2, s[28:29]
	v_lshl_add_u64 v[54:55], s[6:7], 0, v[62:63]
	v_lshlrev_b32_e32 v56, 16, v232
	v_and_b32_e32 v57, 0xffff0000, v232
	v_lshlrev_b32_e32 v48, 16, v233
	v_and_b32_e32 v49, 0xffff0000, v233
	v_lshlrev_b32_e32 v58, 16, v234
	v_and_b32_e32 v59, 0xffff0000, v234
	v_lshlrev_b32_e32 v50, 16, v235
	v_and_b32_e32 v51, 0xffff0000, v235
	v_pk_fma_f32 v[46:47], v[46:47], 0.5, v[48:49] op_sel_hi:[1,0,1]
	v_pk_fma_f32 v[44:45], v[44:45], 0.5, v[56:57] op_sel_hi:[1,0,1]
	v_pk_fma_f32 v[42:43], v[42:43], 0.5, v[50:51] op_sel_hi:[1,0,1]
	v_pk_fma_f32 v[40:41], v[40:41], 0.5, v[58:59] op_sel_hi:[1,0,1]
	global_store_dwordx4 v[52:53], v[44:47], off
	global_store_dwordx4 v[52:53], v[40:43], off offset:16
	s_nop 0
	v_lshl_add_u64 v[44:45], v[144:145], 0, s[18:19]
	v_lshlrev_b64 v[46:47], 1, v[44:45]
	v_lshl_add_u64 v[48:49], s[6:7], 0, v[46:47]
	v_or_b32_e32 v46, 0x100, v46
	v_lshlrev_b32_e32 v50, 16, v236
	v_and_b32_e32 v51, 0xffff0000, v236
	v_lshlrev_b32_e32 v40, 16, v237
	v_and_b32_e32 v41, 0xffff0000, v237
	v_lshlrev_b32_e32 v54, 16, v238
	v_and_b32_e32 v55, 0xffff0000, v238
	v_lshlrev_b32_e32 v42, 16, v239
	v_and_b32_e32 v43, 0xffff0000, v239
	v_pk_fma_f32 v[38:39], v[38:39], 0.5, v[40:41] op_sel_hi:[1,0,1]
	v_pk_fma_f32 v[36:37], v[36:37], 0.5, v[50:51] op_sel_hi:[1,0,1]
	v_pk_fma_f32 v[34:35], v[34:35], 0.5, v[42:43] op_sel_hi:[1,0,1]
	v_pk_fma_f32 v[32:33], v[32:33], 0.5, v[54:55] op_sel_hi:[1,0,1]
	global_store_dwordx4 v[52:53], v[36:39], off offset:512
	global_store_dwordx4 v[52:53], v[32:35], off offset:528
	s_nop 0
	v_lshl_add_u64 v[36:37], v[44:45], 2, s[28:29]
	v_lshl_add_u64 v[38:39], s[6:7], 0, v[46:47]
	v_lshlrev_b32_e32 v40, 16, v240
	v_and_b32_e32 v41, 0xffff0000, v240
	v_lshlrev_b32_e32 v32, 16, v241
	v_and_b32_e32 v33, 0xffff0000, v241
	v_lshlrev_b32_e32 v42, 16, v242
	v_and_b32_e32 v43, 0xffff0000, v242
	v_lshlrev_b32_e32 v34, 16, v243
	v_and_b32_e32 v35, 0xffff0000, v243
	v_pk_fma_f32 v[30:31], v[30:31], 0.5, v[32:33] op_sel_hi:[1,0,1]
	v_pk_fma_f32 v[28:29], v[28:29], 0.5, v[40:41] op_sel_hi:[1,0,1]
	v_pk_fma_f32 v[26:27], v[26:27], 0.5, v[34:35] op_sel_hi:[1,0,1]
	v_pk_fma_f32 v[24:25], v[24:25], 0.5, v[42:43] op_sel_hi:[1,0,1]
	global_store_dwordx4 v[36:37], v[28:31], off
	global_store_dwordx4 v[36:37], v[24:27], off offset:16
	s_nop 0
	v_lshl_add_u64 v[28:29], v[144:145], 0, s[20:21]
	v_lshlrev_b64 v[30:31], 1, v[28:29]
	v_lshl_add_u64 v[32:33], s[6:7], 0, v[30:31]
	v_or_b32_e32 v30, 0x100, v30
	v_lshlrev_b32_e32 v34, 16, v244
	v_and_b32_e32 v35, 0xffff0000, v244
	v_lshlrev_b32_e32 v24, 16, v245
	v_and_b32_e32 v25, 0xffff0000, v245
	v_lshlrev_b32_e32 v38, 16, v246
	v_and_b32_e32 v39, 0xffff0000, v246
	v_lshlrev_b32_e32 v26, 16, v247
	v_and_b32_e32 v27, 0xffff0000, v247
	v_pk_fma_f32 v[22:23], v[22:23], 0.5, v[24:25] op_sel_hi:[1,0,1]
	v_pk_fma_f32 v[20:21], v[20:21], 0.5, v[34:35] op_sel_hi:[1,0,1]
	v_pk_fma_f32 v[18:19], v[18:19], 0.5, v[26:27] op_sel_hi:[1,0,1]
	v_pk_fma_f32 v[16:17], v[16:17], 0.5, v[38:39] op_sel_hi:[1,0,1]
	global_store_dwordx4 v[36:37], v[20:23], off offset:512
	global_store_dwordx4 v[36:37], v[16:19], off offset:528
	s_nop 0
	v_lshl_add_u64 v[20:21], v[28:29], 2, s[28:29]
	v_lshl_add_u64 v[22:23], s[6:7], 0, v[30:31]
	v_lshlrev_b32_e32 v24, 16, v248
	v_and_b32_e32 v25, 0xffff0000, v248
	v_lshlrev_b32_e32 v16, 16, v249
	v_and_b32_e32 v17, 0xffff0000, v249
	v_lshlrev_b32_e32 v26, 16, v250
	v_and_b32_e32 v27, 0xffff0000, v250
	v_lshlrev_b32_e32 v18, 16, v251
	v_and_b32_e32 v19, 0xffff0000, v251
	v_pk_fma_f32 v[14:15], v[14:15], 0.5, v[16:17] op_sel_hi:[1,0,1]
	v_pk_fma_f32 v[12:13], v[12:13], 0.5, v[24:25] op_sel_hi:[1,0,1]
	v_pk_fma_f32 v[10:11], v[10:11], 0.5, v[18:19] op_sel_hi:[1,0,1]
	v_pk_fma_f32 v[8:9], v[8:9], 0.5, v[26:27] op_sel_hi:[1,0,1]
	global_store_dwordx4 v[20:21], v[12:15], off
	global_store_dwordx4 v[20:21], v[8:11], off offset:16
	s_nop 0
	v_lshlrev_b32_e32 v12, 16, v252
	v_and_b32_e32 v13, 0xffff0000, v252
	v_lshlrev_b32_e32 v8, 16, v253
	v_and_b32_e32 v9, 0xffff0000, v253
	v_lshlrev_b32_e32 v14, 16, v254
	v_and_b32_e32 v15, 0xffff0000, v254
	v_lshlrev_b32_e32 v10, 16, v255
	v_and_b32_e32 v11, 0xffff0000, v255
	v_pk_fma_f32 v[6:7], v[6:7], 0.5, v[8:9] op_sel_hi:[1,0,1]
	v_pk_fma_f32 v[4:5], v[4:5], 0.5, v[12:13] op_sel_hi:[1,0,1]
	v_pk_fma_f32 v[2:3], v[2:3], 0.5, v[10:11] op_sel_hi:[1,0,1]
	v_pk_fma_f32 v[0:1], v[0:1], 0.5, v[14:15] op_sel_hi:[1,0,1]
	global_store_dwordx4 v[20:21], v[4:7], off offset:512
	global_store_dwordx4 v[20:21], v[0:3], off offset:528
	s_cbranch_vccnz .LBB0_1890
	s_andn2_b64 vcc, exec, s[4:5]
	s_cbranch_vccnz .LBB0_1889
	s_barrier
	s_branch .LBB0_1889
